# v16 cache hints on top of the v9 P4 de-waterfall (second q/k request and V rows issued earlier)
# speedup vs baseline: 1.0031x; 1.0031x over previous
; __device__ __forceinline__ u32x4 ws_load16(const WsRef& w, unsigned byte_off) { return __builtin_bit_cast(u32x4, __builtin_amdgcn_raw_buffer_load_b128(w.r, byte_off, 0, 0)); }
; __device__ __forceinline__ float log_sigmoid(float x) { return -log1pf(expf(-x)); }
; __device__ __forceinline__ void ret_unit(LAS unsigned char* lds, int u, const bf16* PROJ, const int* pos, const float* dec_f, const float* dec_b, const bf16* ST,
;                                          const float* gn_w, const float* gn_b, bf16* MIX, int tid, const WsRef& wsr) {
;     ...
;     const float lgf2 = log_sigmoid(dec_f[h]) * LOG2E, lgb2 = log_sigmoid(dec_b[h]) * LOG2E;
;     const u32x4* sfp = (const u32x4*)(ST + ((size_t)bh * 64 + c) * 16384); const u32x4* sbp = (const u32x4*)(ST + ((size_t)(8 + bh) * 64 + c) * 16384);
;     u32x4 sf[4], sb[4];
; #pragma unroll
;     for (int i = 0; i < 4; ++i) { sf[i] = sfp[tid + 512 * i]; sb[i] = sbp[tid + 512 * i]; }
;     u32x4 rq1[2], rq2[2], rk1[2], rk2[2], rv[4]; float rp[2];
; #pragma unroll
;     for (int ii = 0; ii < 2; ++ii) { const int it = tid + 512 * ii, dc = it & 7, j = it >> 3; const unsigned qo = (unsigned)WS_PROJ + (unsigned)(((unsigned)(row0 + j) * INC + h * 128 + dc * 8) * 2u);
;         rq1[ii] = ws_load16(wsr, qo); rq2[ii] = ws_load16(wsr, qo + 128u); rk1[ii] = ws_load16(wsr, qo + 1024u); rk2[ii] = ws_load16(wsr, qo + 1152u); rp[ii] = (float)pos[row0 + j]; }
.LBB0_438:
	s_ashr_i32 s0, s73, 6
	s_and_b32 s80, s0, 3
	s_lshl_b32 s1, s80, 2
	v_mov_b32_e32 v86, s1
	global_load_dword v68, v86, s[18:19]
	global_load_dword v87, v86, s[20:21]
	s_and_b32 s82, s73, 63
	s_ashr_i32 s4, s73, 8
	s_ashr_i32 s5, s4, 31
	s_lshl_b32 s81, s82, 7
	s_ashr_i32 s1, s0, 31
	s_lshl_b64 s[0:1], s[0:1], 21
	s_add_u32 s0, s54, s0
	s_addc_u32 s1, s55, s1
	s_mov_b32 s88, s84
	s_movk_i32 s8, 0x2000
	s_lshl_b32 s68, s82, 15
	s_add_u32 s0, s0, s68
	s_addc_u32 s1, s1, 0
	s_add_u32 s82, s0, 0x1000000
	v_lshl_add_u64 v[2:3], s[0:1], 0, v[96:97]
	s_addc_u32 s83, s1, 0
	v_add_co_u32_e64 v8, s[68:69], s8, v2
	v_lshl_add_u64 v[28:29], s[82:83], 0, v[96:97]
	s_nop 0
	v_addc_co_u32_e64 v9, s[68:69], 0, v3, s[68:69]
	v_add_co_u32_e64 v16, s[68:69], s8, v28
	global_load_dwordx4 v[4:7], v96, s[0:1] nt
	global_load_dwordx4 v[12:15], v96, s[82:83] nt
	v_addc_co_u32_e64 v17, s[68:69], 0, v29, s[68:69]
	global_load_dwordx4 v[8:11], v[8:9], off nt
	s_nop 0
	global_load_dwordx4 v[16:19], v[16:17], off nt
	s_nop 0
	global_load_dwordx4 v[24:27], v224, s[0:1] nt
	global_load_dwordx4 v[20:23], v224, s[82:83] nt
	s_movk_i32 s0, 0x6000
	v_add_co_u32_e64 v2, s[68:69], s0, v2
	s_lshl_b64 s[4:5], s[4:5], 13
	s_nop 0
	v_addc_co_u32_e64 v3, s[68:69], 0, v3, s[68:69]
	global_load_dwordx4 v[32:35], v[2:3], off nt
	v_add_co_u32_e64 v2, s[68:69], s0, v28
	s_or_b32 s4, s4, s81
	s_nop 0
	v_addc_co_u32_e64 v3, s[68:69], 0, v29, s[68:69]
	s_lshl_b32 s0, s80, 7
	v_or_b32_e32 v0, s4, v98
	global_load_dwordx4 v[36:39], v[2:3], off nt
	v_or_b32_e32 v2, s0, v106
	v_mul_lo_u32 v3, v0, s9
	v_mov_b32_e32 v1, s5
	v_or_b32_e32 v3, v3, v2
	v_lshl_add_u32 v3, v3, 1, v229
	v_lshl_add_u64 v[0:1], v[0:1], 2, s[12:13]
	buffer_load_dwordx4 v[50:53], v3, s[88:91], 0 offen nt
	buffer_load_dwordx4 v[54:57], v3, s[88:91], 0 offen offset:128 nt
	buffer_load_dwordx4 v[58:61], v3, s[88:91], 0 offen offset:1024 nt
	buffer_load_dwordx4 v[62:65], v3, s[88:91], 0 offen offset:1152 nt
	v_lshl_add_u64 v[66:67], s[4:5], 0, v[100:101]
	global_load_dword v0, v[0:1], off
	v_mul_lo_u32 v204, v66, s9
	v_or_b32_e32 v204, v204, v2
	v_lshl_add_u32 v204, v204, 1, v229
	v_lshl_add_u64 v[66:67], v[66:67], 2, s[12:13]
	buffer_load_dwordx4 v[44:47], v204, s[88:91], 0 offen nt
	buffer_load_dwordx4 v[40:43], v204, s[88:91], 0 offen offset:128 nt
	buffer_load_dwordx4 v[28:31], v204, s[88:91], 0 offen offset:1024 nt
	buffer_load_dwordx4 v[240:243], v204, s[88:91], 0 offen offset:1152 nt
	global_load_dword v66, v[66:67], off
	s_waitcnt vmcnt(18)
	s_add_i32 s101, s80, 1
	s_cmp_eq_u32 s100, s101
	s_cbranch_scc0 .Lp4_log
	v_mov_b32_e32 v48, s98
	v_mov_b32_e32 v105, s99
	s_branch .Lp4_logdone

; __device__ __forceinline__ unsigned pk2(float lo, float hi) { return pg8::cvt_pk_bf16(lo, hi); }
; __device__ __forceinline__ float bflo(unsigned w) { return __uint_as_float(w << 16); }
; __device__ __forceinline__ float bfhi(unsigned w) { return __uint_as_float(w & 0xffff0000u); }
; __device__ __forceinline__ float fexp2(float x) { return __builtin_amdgcn_exp2f(x); }
; __device__ __forceinline__ void ret_unit(LAS unsigned char* lds, int u, const bf16* PROJ, const int* pos, const float* dec_f, const float* dec_b, const bf16* ST,
;                                          const float* gn_w, const float* gn_b, bf16* MIX, int tid, const WsRef& wsr) {
;     ...
;     for (int ii = 0; ii < 2; ++ii) { const int it = tid + 512 * ii, dc = it & 7, j = it >> 3;
;         const u32x4 q1 = rq1[ii], q2 = rq2[ii], k1 = rk1[ii], k2 = rk2[ii];
;         const float p = rp[ii];
;         float sn[8], cs[8];
; #pragma unroll
;         for (int e = 0; e < 8; ++e) { const int i = dc * 8 + e; const float inv = fexp2(-(float)i * 0.20762050593046015f); fast_sincos(p * inv, sn[e], cs[e]); }
;         u32x4 oq1, oq2, ok1, ok2;
; #pragma unroll
;         for (int e = 0; e < 4; ++e) { const int e0 = 2 * e, e1 = 2 * e + 1;
;             const float a0 = bflo(q1[e]), a1 = bfhi(q1[e]), b0 = bflo(q2[e]), b1 = bfhi(q2[e]);
;             oq1[e] = pk2(a0 * cs[e0] - b0 * sn[e0], a1 * cs[e1] - b1 * sn[e1]); oq2[e] = pk2(b0 * cs[e0] + a0 * sn[e0], b1 * cs[e1] + a1 * sn[e1]);
;             const float c0 = bflo(k1[e]) * 0.08838834764831845f, c1 = bfhi(k1[e]) * 0.08838834764831845f, d0 = bflo(k2[e]) * 0.08838834764831845f, d1 = bfhi(k2[e]) * 0.08838834764831845f;
;             ok1[e] = pk2(c0 * cs[e0] - d0 * sn[e0], c1 * cs[e1] - d1 * sn[e1]); ok2[e] = pk2(d0 * cs[e0] + c0 * sn[e0], d1 * cs[e1] + c1 * sn[e1]); }
;     ...
;         for (int r = 0; r < 4; ++r) { const int key = n * 16 + 4 * fq + r; const int df = q - key; const float f = df >= 0 ? fexp2(lgf2 * (float)df) : fexp2(lgb2 * (float)(-df)); s[n][r] *= f; } }
.Lp4_logdone:
	v_mul_f32_e32 v230, 0xbfb8aa3b, v48
	v_cndmask_b32_e64 v89, v105, v230, s[30:31]
	v_cndmask_b32_e64 v94, v105, v230, s[56:57]
	v_cndmask_b32_e64 v95, v105, v230, s[58:59]
	v_mul_f32_e32 v89, v89, v137
	v_cndmask_b32_e64 v92, v105, v230, s[74:75]
	v_cndmask_b32_e64 v93, v105, v230, s[76:77]
	v_mul_f32_e32 v94, v94, v142
	v_mul_f32_e32 v95, v95, v143
	v_exp_f32_e32 v89, v89
	v_mul_f32_e32 v92, v92, v140
	v_mul_f32_e32 v93, v93, v141
	v_exp_f32_e32 v94, v94
	v_exp_f32_e32 v95, v95
	v_exp_f32_e32 v92, v92
	v_exp_f32_e32 v93, v93
	v_cndmask_b32_e64 v130, v105, v230, s[60:61]
	v_cndmask_b32_e64 v131, v105, v230, s[62:63]
	v_cndmask_b32_e64 v48, v105, v230, s[42:43]
	v_mul_f32_e32 v130, v130, v144
	v_mul_f32_e32 v131, v131, v145
	v_mul_f32_e32 v48, v48, v127
	v_exp_f32_e32 v130, v130
	v_exp_f32_e32 v131, v131
	v_exp_f32_e32 v48, v48
	v_cndmask_b32_e64 v90, v105, v230, s[34:35]
	v_cndmask_b32_e64 v91, v105, v230, s[38:39]
	v_mul_f32_e32 v90, v90, v138
	v_mul_f32_e32 v91, v91, v139
	v_exp_f32_e32 v90, v90
	v_exp_f32_e32 v91, v91
	v_cndmask_b32_e64 v238, v105, v230, s[94:95]
	v_mul_f32_e32 v238, v238, v154
	v_exp_f32_e32 v238, v238
	v_cndmask_b32_e64 v234, v105, v230, s[78:79]
	v_cndmask_b32_e64 v235, v105, v230, s[2:3]
	v_cndmask_b32_e64 v236, v105, v230, s[92:93]
	v_cndmask_b32_e32 v237, v105, v230, vcc
	v_mul_f32_e32 v234, v234, v150
	v_mul_f32_e32 v235, v235, v151
	v_mul_f32_e32 v236, v236, v152
	v_mul_f32_e32 v237, v237, v153
	v_exp_f32_e32 v234, v234
	v_exp_f32_e32 v235, v235
	v_exp_f32_e32 v236, v236
	v_exp_f32_e32 v237, v237
	v_cndmask_b32_e64 v132, v105, v230, s[64:65]
	v_cndmask_b32_e64 v133, v105, v230, s[14:15]
	v_cndmask_b32_e64 v232, v105, v230, s[16:17]
	v_cndmask_b32_e64 v233, v105, v230, s[24:25]
	v_mul_f32_e32 v132, v132, v146
	v_mul_f32_e32 v133, v133, v147
	v_mul_f32_e32 v232, v232, v148
	v_mul_f32_e32 v233, v233, v149
	v_exp_f32_e32 v132, v132
	v_exp_f32_e32 v133, v133
	v_exp_f32_e32 v232, v232
	v_exp_f32_e32 v233, v233
	s_mov_b32 s1, 0x800000
	s_add_i32 s73, s73, s40
	s_cmpk_lt_i32 s73, 0x200
	s_waitcnt vmcnt(9)
	v_lshlrev_b32_e32 v82, 16, v50
	s_waitcnt vmcnt(8)
	v_lshlrev_b32_e32 v84, 16, v54
	v_and_b32_e32 v85, 0xffff0000, v54
	v_and_b32_e32 v83, 0xffff0000, v50
	s_waitcnt vmcnt(5)
	v_cvt_f32_i32_e32 v49, v0
	v_mul_f32_e32 v70, v109, v49
	v_mul_f32_e32 v71, 0.15915494, v70
	v_rndne_f32_e32 v71, v71
	v_fmac_f32_e32 v70, 0xc0c90000, v71
	v_fmac_f32_e32 v70, 0xbafdaa22, v71
	v_mul_f32_e32 v71, 0.15915494, v70
	v_sin_f32_e32 v70, v71
	v_cos_f32_e32 v72, v71
	v_mul_f32_e32 v71, v110, v49
	v_mul_f32_e32 v73, 0.15915494, v71
	v_mul_f32_e32 v74, v111, v49
	v_rndne_f32_e32 v73, v73
	v_mul_f32_e32 v75, 0.15915494, v74
	v_fmac_f32_e32 v71, 0xc0c90000, v73
	v_rndne_f32_e32 v75, v75
	v_fmac_f32_e32 v71, 0xbafdaa22, v73
	v_fmac_f32_e32 v74, 0xc0c90000, v75
	v_mul_f32_e32 v73, 0.15915494, v71
	v_fmac_f32_e32 v74, 0xbafdaa22, v75
	v_sin_f32_e32 v71, v73
	v_mul_f32_e32 v75, 0.15915494, v74
	v_cos_f32_e32 v73, v73
	v_sin_f32_e32 v74, v75
	v_cos_f32_e32 v76, v75
	v_mul_f32_e32 v75, v112, v49
	v_mul_f32_e32 v77, 0.15915494, v75
	v_rndne_f32_e32 v77, v77
	v_mul_f32_e32 v78, v113, v49
	v_fmac_f32_e32 v75, 0xc0c90000, v77
	v_mul_f32_e32 v79, 0.15915494, v78
	v_fmac_f32_e32 v75, 0xbafdaa22, v77
	v_rndne_f32_e32 v79, v79
	v_mul_f32_e32 v77, 0.15915494, v75
	v_fmac_f32_e32 v78, 0xc0c90000, v79
	v_sin_f32_e32 v75, v77
	v_fmac_f32_e32 v78, 0xbafdaa22, v79
	v_cos_f32_e32 v77, v77
	v_mul_f32_e32 v79, 0.15915494, v78
	v_sin_f32_e32 v78, v79
	v_cos_f32_e32 v80, v79
	s_waitcnt vmcnt(0)
	v_cvt_f32_i32_e32 v88, v66
	v_mul_f32_e32 v66, v107, v49
	v_mul_f32_e32 v67, 0.15915494, v66
	v_rndne_f32_e32 v67, v67
	v_fmac_f32_e32 v66, 0xc0c90000, v67
	v_fmac_f32_e32 v66, 0xbafdaa22, v67
	v_mul_f32_e32 v67, 0.15915494, v66
	v_sin_f32_e32 v66, v67
	v_cos_f32_e32 v68, v67
	v_mul_f32_e32 v67, v108, v49
	v_mul_f32_e32 v69, 0.15915494, v67
	v_rndne_f32_e32 v69, v69
	v_fmac_f32_e32 v67, 0xc0c90000, v69
	v_fmac_f32_e32 v67, 0xbafdaa22, v69
	v_mul_f32_e32 v69, 0.15915494, v67
	v_sin_f32_e32 v67, v69
	v_cos_f32_e32 v69, v69
	v_mul_f32_e32 v49, v114, v49
	v_mul_f32_e32 v79, 0.15915494, v49
	v_pk_mul_f32 v[86:87], v[66:67], v[84:85]
	v_rndne_f32_e32 v79, v79
	v_pk_fma_f32 v[86:87], v[68:69], v[82:83], v[86:87] neg_lo:[0,0,1] neg_hi:[0,0,1]
	v_pk_mul_f32 v[82:83], v[66:67], v[82:83]
	v_cvt_pk_bf16_f32 v50, v86, v87
	v_pk_fma_f32 v[82:83], v[68:69], v[84:85], v[82:83]
	v_lshlrev_b32_e32 v84, 16, v62
	v_cvt_pk_bf16_f32 v54, v82, v83
	v_lshlrev_b32_e32 v82, 16, v58
	v_and_b32_e32 v83, 0xffff0000, v58
	v_and_b32_e32 v85, 0xffff0000, v62
	v_pk_mul_f32 v[82:83], v[82:83], s[10:11] op_sel_hi:[1,0]
	v_pk_mul_f32 v[84:85], v[84:85], s[10:11] op_sel_hi:[1,0]
	v_fmac_f32_e32 v49, 0xc0c90000, v79
	v_pk_mul_f32 v[86:87], v[84:85], v[66:67]
	v_pk_mul_f32 v[66:67], v[82:83], v[66:67]
	v_pk_fma_f32 v[86:87], v[82:83], v[68:69], v[86:87] neg_lo:[0,0,1] neg_hi:[0,0,1]
	v_pk_fma_f32 v[66:67], v[84:85], v[68:69], v[66:67]
	v_lshlrev_b32_e32 v68, 16, v55
	v_and_b32_e32 v69, 0xffff0000, v55
	v_cvt_pk_bf16_f32 v62, v66, v67
	v_lshlrev_b32_e32 v66, 16, v51
	v_and_b32_e32 v67, 0xffff0000, v51
	v_pk_mul_f32 v[82:83], v[70:71], v[68:69]
	v_fmac_f32_e32 v49, 0xbafdaa22, v79
	v_pk_fma_f32 v[82:83], v[72:73], v[66:67], v[82:83] neg_lo:[0,0,1] neg_hi:[0,0,1]
	v_pk_mul_f32 v[66:67], v[70:71], v[66:67]
	v_cvt_pk_bf16_f32 v51, v82, v83
	v_pk_fma_f32 v[66:67], v[72:73], v[68:69], v[66:67]
	v_lshlrev_b32_e32 v68, 16, v63
	v_and_b32_e32 v69, 0xffff0000, v63
	v_cvt_pk_bf16_f32 v55, v66, v67
	v_lshlrev_b32_e32 v66, 16, v59
	v_and_b32_e32 v67, 0xffff0000, v59
	v_pk_mul_f32 v[68:69], v[68:69], s[10:11] op_sel_hi:[1,0]
; #define LAS __attribute__((address_space(3)))
; __device__ __forceinline__ unsigned pk2(float lo, float hi) { return pg8::cvt_pk_bf16(lo, hi); }
; __device__ __forceinline__ float bflo(unsigned w) { return __uint_as_float(w << 16); }
; __device__ __forceinline__ float bfhi(unsigned w) { return __uint_as_float(w & 0xffff0000u); }
; __device__ __forceinline__ u32x4 ws_load16(const WsRef& w, unsigned byte_off) { return __builtin_bit_cast(u32x4, __builtin_amdgcn_raw_buffer_load_b128(w.r, byte_off, 0, 0)); }
; __device__ __forceinline__ void ret_unit(LAS unsigned char* lds, int u, const bf16* PROJ, const int* pos, const float* dec_f, const float* dec_b, const bf16* ST,
;                                          const float* gn_w, const float* gn_b, bf16* MIX, int tid, const WsRef& wsr) {
;     ...
;     for (int ii = 0; ii < 2; ++ii) { const int it = tid + 512 * ii, dc = it & 7, j = it >> 3;
;         const u32x4 q1 = rq1[ii], q2 = rq2[ii], k1 = rk1[ii], k2 = rk2[ii];
;         const float p = rp[ii];
;         float sn[8], cs[8];
; #pragma unroll
;         for (int e = 0; e < 8; ++e) { const int i = dc * 8 + e; const float inv = fexp2(-(float)i * 0.20762050593046015f); fast_sincos(p * inv, sn[e], cs[e]); }
;         u32x4 oq1, oq2, ok1, ok2;
; #pragma unroll
;         for (int e = 0; e < 4; ++e) { const int e0 = 2 * e, e1 = 2 * e + 1;
;             const float a0 = bflo(q1[e]), a1 = bfhi(q1[e]), b0 = bflo(q2[e]), b1 = bfhi(q2[e]);
;             oq1[e] = pk2(a0 * cs[e0] - b0 * sn[e0], a1 * cs[e1] - b1 * sn[e1]); oq2[e] = pk2(b0 * cs[e0] + a0 * sn[e0], b1 * cs[e1] + a1 * sn[e1]);
;             const float c0 = bflo(k1[e]) * 0.08838834764831845f, c1 = bfhi(k1[e]) * 0.08838834764831845f, d0 = bflo(k2[e]) * 0.08838834764831845f, d1 = bfhi(k2[e]) * 0.08838834764831845f;
;             ok1[e] = pk2(c0 * cs[e0] - d0 * sn[e0], c1 * cs[e1] - d1 * sn[e1]); ok2[e] = pk2(d0 * cs[e0] + c0 * sn[e0], d1 * cs[e1] + c1 * sn[e1]); }
;         *(LAS u32x4*)(Qs + j * LDT + dc * 8) = oq1; *(LAS u32x4*)(Qs + j * LDT + 64 + dc * 8) = oq2;
;         *(LAS u32x4*)(Ks + j * LDT + dc * 8) = ok1; *(LAS u32x4*)(Ks + j * LDT + 64 + dc * 8) = ok2; }
; #pragma unroll
;     for (int ii = 0; ii < 4; ++ii) { const int it = tid + 512 * ii, ec = it & 15, j = it >> 4; rv[ii] = ws_load16(wsr, (unsigned)WS_PROJ + (unsigned)(((unsigned)(row0 + j) * INC + 1024 + h * 128 + ec * 8) * 2u)); }
	v_pk_mul_f32 v[66:67], v[66:67], s[10:11] op_sel_hi:[1,0]
	v_pk_mul_f32 v[82:83], v[68:69], v[70:71]
	v_mul_f32_e32 v49, 0.15915494, v49
	v_pk_fma_f32 v[82:83], v[66:67], v[72:73], v[82:83] neg_lo:[0,0,1] neg_hi:[0,0,1]
	v_pk_mul_f32 v[66:67], v[66:67], v[70:71]
	v_sin_f32_e32 v79, v49
	v_pk_fma_f32 v[66:67], v[68:69], v[72:73], v[66:67]
	v_lshlrev_b32_e32 v68, 16, v56
	v_and_b32_e32 v69, 0xffff0000, v56
	v_cvt_pk_bf16_f32 v63, v66, v67
	v_lshlrev_b32_e32 v66, 16, v52
	v_and_b32_e32 v67, 0xffff0000, v52
	v_pk_mul_f32 v[70:71], v[74:75], v[68:69]
	v_cos_f32_e32 v81, v49
	v_pk_fma_f32 v[70:71], v[76:77], v[66:67], v[70:71] neg_lo:[0,0,1] neg_hi:[0,0,1]
	v_pk_mul_f32 v[66:67], v[74:75], v[66:67]
	v_cvt_pk_bf16_f32 v52, v70, v71
	v_pk_fma_f32 v[66:67], v[76:77], v[68:69], v[66:67]
	v_lshlrev_b32_e32 v68, 16, v64
	v_and_b32_e32 v69, 0xffff0000, v64
	v_cvt_pk_bf16_f32 v56, v66, v67
	v_lshlrev_b32_e32 v66, 16, v60
	v_and_b32_e32 v67, 0xffff0000, v60
	v_pk_mul_f32 v[68:69], v[68:69], s[10:11] op_sel_hi:[1,0]
	v_pk_mul_f32 v[66:67], v[66:67], s[10:11] op_sel_hi:[1,0]
	v_pk_mul_f32 v[70:71], v[68:69], v[74:75]
	v_mul_f32_e32 v49, v107, v88
	v_pk_fma_f32 v[70:71], v[66:67], v[76:77], v[70:71] neg_lo:[0,0,1] neg_hi:[0,0,1]
	v_pk_mul_f32 v[66:67], v[66:67], v[74:75]
	v_cvt_pk_bf16_f32 v60, v70, v71
	v_pk_fma_f32 v[66:67], v[68:69], v[76:77], v[66:67]
	v_lshlrev_b32_e32 v68, 16, v57
	v_and_b32_e32 v69, 0xffff0000, v57
	v_cvt_pk_bf16_f32 v64, v66, v67
	v_lshlrev_b32_e32 v66, 16, v53
	v_and_b32_e32 v67, 0xffff0000, v53
	v_pk_mul_f32 v[70:71], v[78:79], v[68:69]
	v_cvt_pk_bf16_f32 v58, v86, v87
	v_pk_fma_f32 v[70:71], v[80:81], v[66:67], v[70:71] neg_lo:[0,0,1] neg_hi:[0,0,1]
	v_pk_mul_f32 v[66:67], v[78:79], v[66:67]
	v_cvt_pk_bf16_f32 v53, v70, v71
	v_pk_fma_f32 v[66:67], v[80:81], v[68:69], v[66:67]
	v_lshlrev_b32_e32 v68, 16, v65
	v_and_b32_e32 v69, 0xffff0000, v65
	v_cvt_pk_bf16_f32 v57, v66, v67
	v_lshlrev_b32_e32 v66, 16, v61
	v_and_b32_e32 v67, 0xffff0000, v61
	v_pk_mul_f32 v[68:69], v[68:69], s[10:11] op_sel_hi:[1,0]
	v_pk_mul_f32 v[66:67], v[66:67], s[10:11] op_sel_hi:[1,0]
	v_pk_mul_f32 v[70:71], v[68:69], v[78:79]
	v_cvt_pk_bf16_f32 v59, v82, v83
	v_pk_fma_f32 v[70:71], v[66:67], v[80:81], v[70:71] neg_lo:[0,0,1] neg_hi:[0,0,1]
	v_pk_mul_f32 v[66:67], v[66:67], v[78:79]
	v_cvt_pk_bf16_f32 v61, v70, v71
	v_pk_fma_f32 v[66:67], v[68:69], v[80:81], v[66:67]
	v_lshlrev_b32_e32 v68, 16, v40
	v_cvt_pk_bf16_f32 v65, v66, v67
	ds_write_b128 v115, v[50:53]
	ds_write_b128 v115, v[54:57] offset:128
	ds_write_b128 v115, v[58:61] offset:34816
	ds_write_b128 v115, v[62:65] offset:34944
	v_or_b32_e32 v87, s0, v222
	v_or_b32_e32 v204, s4, v99
	v_mul_lo_u32 v204, v204, s9
	v_add_lshl_u32 v204, v204, v87, 1
	v_add_u32_e32 v204, v204, v229
	buffer_load_dwordx4 v[72:75], v204, s[88:91], 0 offen nt
	v_or_b32_e32 v239, s4, v117
	v_mul_lo_u32 v239, v239, s9
	v_add_lshl_u32 v239, v239, v87, 1
	v_add_u32_e32 v239, v239, v229
	buffer_load_dwordx4 v[78:81], v239, s[88:91], 0 offen nt
	v_or_b32_e32 v77, s4, v118
	v_mul_lo_u32 v77, v77, s9
	v_add_lshl_u32 v77, v77, v87, 1
	v_add_u32_e32 v77, v77, v229
	buffer_load_dwordx4 v[82:85], v77, s[88:91], 0 offen nt
	v_add_u32_e32 v204, s4, v119
	v_mul_lo_u32 v204, v204, s9
	v_add_lshl_u32 v204, v204, v87, 1
	v_add_u32_e32 v204, v204, v229
	buffer_load_dwordx4 v[248:251], v204, s[88:91], 0 offen nt
	v_mul_f32_e32 v50, 0.15915494, v49
	v_rndne_f32_e32 v50, v50
	v_fmac_f32_e32 v49, 0xc0c90000, v50
	v_fmac_f32_e32 v49, 0xbafdaa22, v50
	v_mul_f32_e32 v49, 0.15915494, v49
	v_sin_f32_e32 v50, v49
	v_cos_f32_e32 v52, v49
	v_mul_f32_e32 v49, v108, v88
	v_mul_f32_e32 v51, 0.15915494, v49
	v_rndne_f32_e32 v51, v51
	v_fmac_f32_e32 v49, 0xc0c90000, v51
	v_fmac_f32_e32 v49, 0xbafdaa22, v51
	v_mul_f32_e32 v49, 0.15915494, v49
	v_sin_f32_e32 v51, v49
	v_cos_f32_e32 v53, v49
	v_mul_f32_e32 v49, v109, v88
	v_mul_f32_e32 v54, 0.15915494, v49
	v_rndne_f32_e32 v54, v54
	v_fmac_f32_e32 v49, 0xc0c90000, v54
	v_fmac_f32_e32 v49, 0xbafdaa22, v54
	v_mul_f32_e32 v49, 0.15915494, v49
	v_sin_f32_e32 v54, v49
	v_cos_f32_e32 v56, v49
	v_mul_f32_e32 v49, v110, v88
	v_mul_f32_e32 v55, 0.15915494, v49
	v_rndne_f32_e32 v55, v55
	v_fmac_f32_e32 v49, 0xc0c90000, v55
	v_fmac_f32_e32 v49, 0xbafdaa22, v55
	v_mul_f32_e32 v49, 0.15915494, v49
	v_sin_f32_e32 v55, v49
	v_cos_f32_e32 v57, v49
	v_mul_f32_e32 v49, v111, v88
	v_mul_f32_e32 v58, 0.15915494, v49
	v_rndne_f32_e32 v58, v58
	v_fmac_f32_e32 v49, 0xc0c90000, v58
	v_fmac_f32_e32 v49, 0xbafdaa22, v58
	v_mul_f32_e32 v49, 0.15915494, v49
	v_sin_f32_e32 v58, v49
	v_cos_f32_e32 v60, v49
	v_mul_f32_e32 v49, v112, v88
	v_and_b32_e32 v69, 0xffff0000, v40
	v_mul_f32_e32 v59, 0.15915494, v49
	v_lshlrev_b32_e32 v66, 16, v44
	v_and_b32_e32 v67, 0xffff0000, v44
	v_pk_mul_f32 v[70:71], v[50:51], v[68:69]
	v_rndne_f32_e32 v59, v59
	v_pk_fma_f32 v[70:71], v[52:53], v[66:67], v[70:71] neg_lo:[0,0,1] neg_hi:[0,0,1]
	v_pk_mul_f32 v[66:67], v[50:51], v[66:67]
	v_fmac_f32_e32 v49, 0xc0c90000, v59
	v_pk_fma_f32 v[66:67], v[52:53], v[68:69], v[66:67]
	v_fmac_f32_e32 v49, 0xbafdaa22, v59
	v_cvt_pk_bf16_f32 v44, v66, v67
	v_lshlrev_b32_e32 v66, 16, v28
	v_and_b32_e32 v67, 0xffff0000, v28
	v_lshlrev_b32_e32 v68, 16, v240
	v_and_b32_e32 v69, 0xffff0000, v240
	v_mul_f32_e32 v49, 0.15915494, v49
	v_pk_mul_f32 v[66:67], v[66:67], s[10:11] op_sel_hi:[1,0]
	v_pk_mul_f32 v[68:69], v[68:69], s[10:11] op_sel_hi:[1,0]
	v_sin_f32_e32 v59, v49
	v_cos_f32_e32 v61, v49
	v_mul_f32_e32 v49, v113, v88
	v_cvt_pk_bf16_f32 v40, v70, v71
	v_pk_mul_f32 v[70:71], v[68:69], v[50:51]
	v_pk_mul_f32 v[50:51], v[66:67], v[50:51]
	v_mul_f32_e32 v62, 0.15915494, v49
; #define LAS __attribute__((address_space(3)))
; __device__ __forceinline__ unsigned pk2(float lo, float hi) { return pg8::cvt_pk_bf16(lo, hi); }
; __device__ __forceinline__ float bflo(unsigned w) { return __uint_as_float(w << 16); }
; __device__ __forceinline__ float bfhi(unsigned w) { return __uint_as_float(w & 0xffff0000u); }
; __device__ __forceinline__ u32x4 ws_load16(const WsRef& w, unsigned byte_off) { return __builtin_bit_cast(u32x4, __builtin_amdgcn_raw_buffer_load_b128(w.r, byte_off, 0, 0)); }
; __device__ __forceinline__ void ret_unit(LAS unsigned char* lds, int u, const bf16* PROJ, const int* pos, const float* dec_f, const float* dec_b, const bf16* ST,
;                                          const float* gn_w, const float* gn_b, bf16* MIX, int tid, const WsRef& wsr) {
;     ...
;         for (int e = 0; e < 4; ++e) { const int e0 = 2 * e, e1 = 2 * e + 1;
;             const float a0 = bflo(q1[e]), a1 = bfhi(q1[e]), b0 = bflo(q2[e]), b1 = bfhi(q2[e]);
;             oq1[e] = pk2(a0 * cs[e0] - b0 * sn[e0], a1 * cs[e1] - b1 * sn[e1]); oq2[e] = pk2(b0 * cs[e0] + a0 * sn[e0], b1 * cs[e1] + a1 * sn[e1]);
;             const float c0 = bflo(k1[e]) * 0.08838834764831845f, c1 = bfhi(k1[e]) * 0.08838834764831845f, d0 = bflo(k2[e]) * 0.08838834764831845f, d1 = bfhi(k2[e]) * 0.08838834764831845f;
;             ok1[e] = pk2(c0 * cs[e0] - d0 * sn[e0], c1 * cs[e1] - d1 * sn[e1]); ok2[e] = pk2(d0 * cs[e0] + c0 * sn[e0], d1 * cs[e1] + c1 * sn[e1]); }
;         *(LAS u32x4*)(Qs + j * LDT + dc * 8) = oq1; *(LAS u32x4*)(Qs + j * LDT + 64 + dc * 8) = oq2;
;         *(LAS u32x4*)(Ks + j * LDT + dc * 8) = ok1; *(LAS u32x4*)(Ks + j * LDT + 64 + dc * 8) = ok2; }
; #pragma unroll
;     for (int ii = 0; ii < 4; ++ii) { const int it = tid + 512 * ii, ec = it & 15, j = it >> 4; rv[ii] = ws_load16(wsr, (unsigned)WS_PROJ + (unsigned)(((unsigned)(row0 + j) * INC + 1024 + h * 128 + ec * 8) * 2u)); }
; #pragma unroll
;     for (int ii = 0; ii < 4; ++ii) { const int it = tid + 512 * ii, ec = it & 15, j = it >> 4; const u32x4 w = rv[ii];
;         const int jsw = (((j >> 3) ^ (ec & 7)) << 3) | (j & 7);
; #pragma unroll
;         for (int e = 0; e < 4; ++e) { VT[(ec * 8 + 2 * e) * LDT + jsw] = (bf16)(w[e] & 0xffffu); VT[(ec * 8 + 2 * e + 1) * LDT + jsw] = (bf16)(w[e] >> 16); } }
	v_pk_fma_f32 v[70:71], v[66:67], v[52:53], v[70:71] neg_lo:[0,0,1] neg_hi:[0,0,1]
	v_pk_fma_f32 v[50:51], v[68:69], v[52:53], v[50:51]
	v_lshlrev_b32_e32 v52, 16, v41
	v_and_b32_e32 v53, 0xffff0000, v41
	v_rndne_f32_e32 v62, v62
	v_cvt_pk_bf16_f32 v28, v50, v51
	v_lshlrev_b32_e32 v50, 16, v45
	v_and_b32_e32 v51, 0xffff0000, v45
	v_pk_mul_f32 v[66:67], v[54:55], v[52:53]
	v_fmac_f32_e32 v49, 0xc0c90000, v62
	v_pk_fma_f32 v[66:67], v[56:57], v[50:51], v[66:67] neg_lo:[0,0,1] neg_hi:[0,0,1]
	v_pk_mul_f32 v[50:51], v[54:55], v[50:51]
	v_fmac_f32_e32 v49, 0xbafdaa22, v62
	v_pk_fma_f32 v[50:51], v[56:57], v[52:53], v[50:51]
	v_lshlrev_b32_e32 v52, 16, v241
	v_and_b32_e32 v53, 0xffff0000, v241
	v_mul_f32_e32 v49, 0.15915494, v49
	v_cvt_pk_bf16_f32 v45, v50, v51
	v_lshlrev_b32_e32 v50, 16, v29
	v_and_b32_e32 v51, 0xffff0000, v29
	v_pk_mul_f32 v[52:53], v[52:53], s[10:11] op_sel_hi:[1,0]
	v_sin_f32_e32 v62, v49
	v_cos_f32_e32 v64, v49
	v_mul_f32_e32 v49, v114, v88
	v_cvt_pk_bf16_f32 v41, v66, v67
	v_pk_mul_f32 v[50:51], v[50:51], s[10:11] op_sel_hi:[1,0]
	v_pk_mul_f32 v[66:67], v[52:53], v[54:55]
	v_mul_f32_e32 v63, 0.15915494, v49
	v_pk_fma_f32 v[66:67], v[50:51], v[56:57], v[66:67] neg_lo:[0,0,1] neg_hi:[0,0,1]
	v_pk_mul_f32 v[50:51], v[50:51], v[54:55]
	v_rndne_f32_e32 v63, v63
	v_pk_fma_f32 v[50:51], v[52:53], v[56:57], v[50:51]
	v_lshlrev_b32_e32 v52, 16, v42
	v_and_b32_e32 v53, 0xffff0000, v42
	v_fmac_f32_e32 v49, 0xc0c90000, v63
	v_cvt_pk_bf16_f32 v29, v50, v51
	v_lshlrev_b32_e32 v50, 16, v46
	v_and_b32_e32 v51, 0xffff0000, v46
	v_pk_mul_f32 v[54:55], v[58:59], v[52:53]
	v_fmac_f32_e32 v49, 0xbafdaa22, v63
	v_pk_fma_f32 v[54:55], v[60:61], v[50:51], v[54:55] neg_lo:[0,0,1] neg_hi:[0,0,1]
	v_pk_mul_f32 v[50:51], v[58:59], v[50:51]
	v_mul_f32_e32 v49, 0.15915494, v49
	v_pk_fma_f32 v[50:51], v[60:61], v[52:53], v[50:51]
	v_lshlrev_b32_e32 v52, 16, v242
	v_and_b32_e32 v53, 0xffff0000, v242
	v_sin_f32_e32 v63, v49
	v_cvt_pk_bf16_f32 v46, v50, v51
	v_lshlrev_b32_e32 v50, 16, v30
	v_and_b32_e32 v51, 0xffff0000, v30
	v_pk_mul_f32 v[52:53], v[52:53], s[10:11] op_sel_hi:[1,0]
	v_cos_f32_e32 v65, v49
	v_cvt_pk_bf16_f32 v42, v54, v55
	v_pk_mul_f32 v[50:51], v[50:51], s[10:11] op_sel_hi:[1,0]
	v_pk_mul_f32 v[54:55], v[52:53], v[58:59]
	v_cvt_pk_bf16_f32 v0, v70, v71
	v_pk_fma_f32 v[54:55], v[50:51], v[60:61], v[54:55] neg_lo:[0,0,1] neg_hi:[0,0,1]
	v_pk_mul_f32 v[50:51], v[50:51], v[58:59]
	v_cvt_pk_bf16_f32 v2, v54, v55
	v_pk_fma_f32 v[50:51], v[52:53], v[60:61], v[50:51]
	v_lshlrev_b32_e32 v52, 16, v43
	v_and_b32_e32 v53, 0xffff0000, v43
	v_cvt_pk_bf16_f32 v30, v50, v51
	v_lshlrev_b32_e32 v50, 16, v47
	v_and_b32_e32 v51, 0xffff0000, v47
	v_pk_mul_f32 v[54:55], v[62:63], v[52:53]
	v_cvt_pk_bf16_f32 v1, v66, v67
	v_pk_fma_f32 v[54:55], v[64:65], v[50:51], v[54:55] neg_lo:[0,0,1] neg_hi:[0,0,1]
	v_pk_mul_f32 v[50:51], v[62:63], v[50:51]
	v_cvt_pk_bf16_f32 v43, v54, v55
	v_pk_fma_f32 v[50:51], v[64:65], v[52:53], v[50:51]
	v_lshlrev_b32_e32 v52, 16, v243
	v_and_b32_e32 v53, 0xffff0000, v243
	v_cvt_pk_bf16_f32 v47, v50, v51
	v_lshlrev_b32_e32 v50, 16, v31
	v_and_b32_e32 v51, 0xffff0000, v31
	v_pk_mul_f32 v[52:53], v[52:53], s[10:11] op_sel_hi:[1,0]
	v_pk_mul_f32 v[50:51], v[50:51], s[10:11] op_sel_hi:[1,0]
	v_pk_mul_f32 v[54:55], v[52:53], v[62:63]
	v_add_u32_e32 v49, v124, v125
	v_pk_fma_f32 v[54:55], v[50:51], v[64:65], v[54:55] neg_lo:[0,0,1] neg_hi:[0,0,1]
	v_pk_mul_f32 v[50:51], v[50:51], v[62:63]
	v_cvt_pk_bf16_f32 v3, v54, v55
	v_pk_fma_f32 v[50:51], v[52:53], v[64:65], v[50:51]
	v_cndmask_b32_e64 v86, v105, v230, s[66:67]
	v_cvt_pk_bf16_f32 v31, v50, v51
	ds_write_b128 v116, v[40:43]
	ds_write_b128 v116, v[44:47] offset:128
	ds_write_b128 v116, v[0:3] offset:34816
	ds_write_b128 v116, v[28:31] offset:34944
	s_waitcnt vmcnt(3)
	ds_write_b16 v120, v72
	ds_write_b16_d16_hi v120, v72 offset:272
	ds_write_b16 v120, v73 offset:544
	ds_write_b16_d16_hi v120, v73 offset:816
	ds_write_b16 v120, v74 offset:1088
	ds_write_b16_d16_hi v120, v74 offset:1360
	ds_write_b16 v120, v75 offset:1632
	ds_write_b16_d16_hi v120, v75 offset:1904
	s_waitcnt vmcnt(2)
	ds_write_b16 v121, v78
	ds_write_b16_d16_hi v121, v78 offset:272
	ds_write_b16 v121, v79 offset:544
	ds_write_b16_d16_hi v121, v79 offset:816
	ds_write_b16 v121, v80 offset:1088
	ds_write_b16_d16_hi v121, v80 offset:1360
	ds_write_b16 v121, v81 offset:1632
	ds_write_b16_d16_hi v121, v81 offset:1904
	s_waitcnt vmcnt(1)
	ds_write_b16 v122, v82
	ds_write_b16_d16_hi v122, v82 offset:272
	ds_write_b16 v122, v83 offset:544
	ds_write_b16_d16_hi v122, v83 offset:816
	ds_write_b16 v122, v84 offset:1088
	ds_write_b16_d16_hi v122, v84 offset:1360
	ds_write_b16 v122, v85 offset:1632
	ds_write_b16_d16_hi v122, v85 offset:1904
	s_waitcnt vmcnt(0)
	ds_write_b16 v123, v248
	ds_write_b16_d16_hi v123, v248 offset:272
	ds_write_b16 v123, v249 offset:544
	ds_write_b16_d16_hi v123, v249 offset:816
	ds_write_b16 v123, v250 offset:1088
	ds_write_b16_d16_hi v123, v250 offset:1360
	ds_write_b16 v123, v251 offset:1632
	ds_write_b16_d16_hi v123, v251 offset:1904
	s_waitcnt lgkmcnt(0)
	s_barrier
; #define LAS __attribute__((address_space(3)))
; __device__ __forceinline__ unsigned pk2(float lo, float hi) { return pg8::cvt_pk_bf16(lo, hi); }
; __device__ __forceinline__ float fexp2(float x) { return __builtin_amdgcn_exp2f(x); }
; #define MFMA16(a, b, c) __builtin_amdgcn_mfma_f32_16x16x32_bf16((a), (b), (c), 0, 0, 0)
; __device__ __forceinline__ void ret_unit(LAS unsigned char* lds, int u, const bf16* PROJ, const int* pos, const float* dec_f, const float* dec_b, const bf16* ST,
;                                          const float* gn_w, const float* gn_b, bf16* MIX, int tid, const WsRef& wsr) {
;     ...
;     const int q = wave * 16 + fr;
;     bf16x8 qf[4];
; #pragma unroll
;     for (int kk = 0; kk < 4; ++kk) qf[kk] = *(const LAS bf16x8*)(Qs + q * LDT + kk * 32 + fq * 8);
;     f32x4 s[8];
; #pragma unroll
;     for (int n = 0; n < 8; ++n) s[n] = (f32x4){0.f, 0.f, 0.f, 0.f};
; #pragma unroll
;     for (int kk = 0; kk < 4; ++kk)
; #pragma unroll
;         for (int n = 0; n < 8; ++n) { const bf16x8 kf = *(const LAS bf16x8*)(Ks + (n * 16 + fr) * LDT + kk * 32 + fq * 8); s[n] = MFMA16(kf, qf[kk], s[n]); }
;     bf16x8 pf[4];
; #pragma unroll
;     for (int n = 0; n < 8; ++n) {
; #pragma unroll
;         for (int r = 0; r < 4; ++r) { const int key = n * 16 + 4 * fq + r; const int df = q - key; const float f = df >= 0 ? fexp2(lgf2 * (float)df) : fexp2(lgb2 * (float)(-df)); s[n][r] *= f; } }
; #pragma unroll
;     for (int kk = 0; kk < 4; ++kk) { u32x4 w; w.x = pk2(s[2 * kk][0], s[2 * kk][1]); w.y = pk2(s[2 * kk][2], s[2 * kk][3]); w.z = pk2(s[2 * kk + 1][0], s[2 * kk + 1][1]); w.w = pk2(s[2 * kk + 1][2], s[2 * kk + 1][3]);
;         pf[kk] = __builtin_bit_cast(bf16x8, w); }
;     f32x4 o[8];
; #pragma unroll
;     for (int n = 0; n < 8; ++n) o[n] = (f32x4){0.f, 0.f, 0.f, 0.f};
; #pragma unroll
;     for (int kk = 0; kk < 4; ++kk)
; #pragma unroll
;         for (int n = 0; n < 8; ++n) { const int sw = (2 * n + (fr >> 3)) & 7, jc = kk * 4 + (fq >> 1); const LAS bf16* vr = VT + (n * 16 + fr) * LDT + 4 * (fq & 1);
;             const u32x2 lo = *(const LAS u32x2*)(vr + ((jc ^ sw) << 3)), hi = *(const LAS u32x2*)(vr + (((jc + 2) ^ sw) << 3)); u32x4 w; w.x = lo.x; w.y = lo.y; w.z = hi.x; w.w = hi.y;
;             o[n] = MFMA16(__builtin_bit_cast(bf16x8, w), pf[kk], o[n]); }
	ds_read_b128 v[44:47], v225
	ds_read_b128 v[40:43], v225 offset:64
	ds_read_b128 v[28:31], v225 offset:128
	ds_read_b128 v[0:3], v225 offset:192
	ds_read_b128 v[50:53], v226 offset:34816
	ds_read_b128 v[54:57], v226 offset:39168
	ds_read_b128 v[82:85], v226 offset:34880
	s_waitcnt lgkmcnt(2)
	v_mfma_f32_16x16x32_bf16 v[50:53], v[50:53], v[44:47], 0
	ds_read_b128 v[58:61], v226 offset:43520
	ds_read_b128 v[62:65], v226 offset:47872
	ds_read_b128 v[66:69], v226 offset:52224
	s_waitcnt lgkmcnt(3)
	v_mfma_f32_16x16x32_bf16 v[50:53], v[82:85], v[40:43], v[50:53]
	ds_read_b128 v[82:85], v226 offset:39232
	ds_read_b128 v[70:73], v49 offset:34816
	ds_read_b128 v[74:77], v49 offset:39168
	v_mfma_f32_16x16x32_bf16 v[54:57], v[54:57], v[44:47], 0
	ds_read_b128 v[78:81], v49 offset:43520
	v_cndmask_b32_e64 v87, v105, v230, s[26:27]
	v_cndmask_b32_e64 v88, v105, v230, s[28:29]
	s_waitcnt lgkmcnt(3)
	v_mfma_f32_16x16x32_bf16 v[54:57], v[82:85], v[40:43], v[54:57]
	ds_read_b128 v[82:85], v226 offset:43584
	v_mul_f32_e32 v86, v86, v134
	v_mul_f32_e32 v87, v87, v135
	v_mfma_f32_16x16x32_bf16 v[58:61], v[58:61], v[44:47], 0
	v_mul_f32_e32 v88, v88, v136
	v_exp_f32_e32 v86, v86
	v_exp_f32_e32 v87, v87
	s_waitcnt lgkmcnt(0)
	v_mfma_f32_16x16x32_bf16 v[58:61], v[82:85], v[40:43], v[58:61]
	ds_read_b128 v[82:85], v226 offset:47936
	v_exp_f32_e32 v88, v88
	v_readlane_b32 s68, v255, 4
	v_mfma_f32_16x16x32_bf16 v[62:65], v[62:65], v[44:47], 0
	v_readlane_b32 s69, v255, 5
	s_waitcnt lgkmcnt(0)
	v_mfma_f32_16x16x32_bf16 v[62:65], v[82:85], v[40:43], v[62:65]
	ds_read_b128 v[82:85], v226 offset:52288
	v_cndmask_b32_e64 v239, v105, v230, s[68:69]
	v_readlane_b32 s68, v255, 50
	v_mfma_f32_16x16x32_bf16 v[66:69], v[66:69], v[44:47], 0
	v_readlane_b32 s69, v255, 51
	v_mul_f32_e32 v239, v239, v155
	v_exp_f32_e32 v239, v239
	s_waitcnt lgkmcnt(0)
	v_mfma_f32_16x16x32_bf16 v[66:69], v[82:85], v[40:43], v[66:69]
	ds_read_b128 v[82:85], v49 offset:34880
	v_cndmask_b32_e64 v240, v105, v230, s[68:69]
	v_readlane_b32 s68, v255, 52
	v_mfma_f32_16x16x32_bf16 v[70:73], v[70:73], v[44:47], 0
	v_readlane_b32 s69, v255, 53
	v_mul_f32_e32 v240, v240, v156
	v_exp_f32_e32 v240, v240
	s_waitcnt lgkmcnt(0)
	v_mfma_f32_16x16x32_bf16 v[70:73], v[82:85], v[40:43], v[70:73]
	ds_read_b128 v[82:85], v49 offset:39232
	v_cndmask_b32_e64 v241, v105, v230, s[68:69]
	v_readlane_b32 s68, v255, 54
	v_mfma_f32_16x16x32_bf16 v[74:77], v[74:77], v[44:47], 0
	v_readlane_b32 s69, v255, 55
	v_mul_f32_e32 v241, v241, v157
	v_exp_f32_e32 v241, v241
	s_waitcnt lgkmcnt(0)
	v_mfma_f32_16x16x32_bf16 v[74:77], v[82:85], v[40:43], v[74:77]
	ds_read_b128 v[82:85], v49 offset:43584
	v_cndmask_b32_e64 v242, v105, v230, s[68:69]
	v_readlane_b32 s68, v255, 56
	v_mfma_f32_16x16x32_bf16 v[78:81], v[78:81], v[44:47], 0
	v_readlane_b32 s69, v255, 57
	v_mul_f32_e32 v242, v242, v158
	v_exp_f32_e32 v242, v242
	s_waitcnt lgkmcnt(0)
	v_mfma_f32_16x16x32_bf16 v[78:81], v[82:85], v[40:43], v[78:81]
	ds_read_b128 v[82:85], v226 offset:34944
	v_cndmask_b32_e64 v243, v105, v230, s[68:69]
	v_mul_f32_e32 v243, v243, v159
	s_waitcnt lgkmcnt(0)
	v_mfma_f32_16x16x32_bf16 v[50:53], v[82:85], v[28:31], v[50:53]
	ds_read_b128 v[82:85], v226 offset:39296
	v_exp_f32_e32 v243, v243
	s_waitcnt lgkmcnt(0)
	v_mfma_f32_16x16x32_bf16 v[54:57], v[82:85], v[28:31], v[54:57]
	ds_read_b128 v[82:85], v226 offset:43648
	s_waitcnt lgkmcnt(0)
	v_mfma_f32_16x16x32_bf16 v[58:61], v[82:85], v[28:31], v[58:61]
	ds_read_b128 v[82:85], v226 offset:48000
	s_waitcnt lgkmcnt(0)
	v_mfma_f32_16x16x32_bf16 v[62:65], v[82:85], v[28:31], v[62:65]
	ds_read_b128 v[82:85], v226 offset:52352
	s_waitcnt lgkmcnt(0)
	v_mfma_f32_16x16x32_bf16 v[66:69], v[82:85], v[28:31], v[66:69]
	ds_read_b128 v[82:85], v49 offset:34944
	s_waitcnt lgkmcnt(0)
	v_mfma_f32_16x16x32_bf16 v[70:73], v[82:85], v[28:31], v[70:73]
	ds_read_b128 v[82:85], v49 offset:39296
	s_waitcnt lgkmcnt(0)
	v_mfma_f32_16x16x32_bf16 v[74:77], v[82:85], v[28:31], v[74:77]
	ds_read_b128 v[82:85], v49 offset:43648
	s_waitcnt lgkmcnt(0)
	v_mfma_f32_16x16x32_bf16 v[78:81], v[82:85], v[28:31], v[78:81]
	ds_read_b128 v[82:85], v226 offset:35008
	s_waitcnt lgkmcnt(0)
	v_mfma_f32_16x16x32_bf16 v[50:53], v[82:85], v[0:3], v[50:53]
	ds_read_b128 v[82:85], v226 offset:39360
	s_waitcnt lgkmcnt(0)
	v_mfma_f32_16x16x32_bf16 v[54:57], v[82:85], v[0:3], v[54:57]
	ds_read_b128 v[82:85], v226 offset:43712
	s_nop 6
	v_pk_mul_f32 v[56:57], v[86:87], v[56:57]
	s_waitcnt lgkmcnt(0)
	v_mfma_f32_16x16x32_bf16 v[58:61], v[82:85], v[0:3], v[58:61]
	ds_read_b128 v[82:85], v226 offset:48064
	s_nop 6
	v_pk_mul_f32 v[58:59], v[88:89], v[58:59]
	s_waitcnt lgkmcnt(0)
	v_mfma_f32_16x16x32_bf16 v[62:65], v[82:85], v[0:3], v[62:65]
	ds_read_b128 v[82:85], v226 offset:52416
	v_pk_mul_f32 v[88:89], v[90:91], v[60:61]
	s_nop 5
	v_pk_mul_f32 v[64:65], v[94:95], v[64:65]
	s_waitcnt lgkmcnt(0)
	v_mfma_f32_16x16x32_bf16 v[66:69], v[82:85], v[0:3], v[66:69]
	ds_read_b128 v[82:85], v49 offset:35008
	v_pk_mul_f32 v[92:93], v[92:93], v[62:63]
	v_cvt_pk_bf16_f32 v63, v56, v57
	v_cvt_pk_bf16_f32 v56, v58, v59
	v_cvt_pk_bf16_f32 v59, v64, v65
	v_add_u32_e32 v64, v160, v161
	ds_read_b64 v[64:65], v64
	s_waitcnt lgkmcnt(1)
	v_mfma_f32_16x16x32_bf16 v[70:73], v[82:85], v[0:3], v[70:73]
	ds_read_b128 v[82:85], v49 offset:39360
	v_cvt_pk_bf16_f32 v58, v92, v93
	v_add_u32_e32 v92, v175, v170
	ds_read_b64 v[92:93], v92
	s_waitcnt lgkmcnt(1)
	v_mfma_f32_16x16x32_bf16 v[74:77], v[82:85], v[0:3], v[74:77]
	ds_read_b128 v[82:85], v49 offset:43712
	v_add_u32_e32 v94, v175, v171
	ds_read_b64 v[94:95], v94
	s_waitcnt lgkmcnt(1)
; #define LAS __attribute__((address_space(3)))
; __device__ __forceinline__ unsigned pk2(float lo, float hi) { return pg8::cvt_pk_bf16(lo, hi); }
; __device__ __forceinline__ float fexp2(float x) { return __builtin_amdgcn_exp2f(x); }
; #define MFMA16(a, b, c) __builtin_amdgcn_mfma_f32_16x16x32_bf16((a), (b), (c), 0, 0, 0)
; __device__ __forceinline__ void ret_unit(LAS unsigned char* lds, int u, const bf16* PROJ, const int* pos, const float* dec_f, const float* dec_b, const bf16* ST,
;                                          const float* gn_w, const float* gn_b, bf16* MIX, int tid, const WsRef& wsr) {
;     ...
;     bf16x8 pf[4];
; #pragma unroll
;     for (int n = 0; n < 8; ++n) {
; #pragma unroll
;         for (int r = 0; r < 4; ++r) { const int key = n * 16 + 4 * fq + r; const int df = q - key; const float f = df >= 0 ? fexp2(lgf2 * (float)df) : fexp2(lgb2 * (float)(-df)); s[n][r] *= f; } }
; #pragma unroll
;     for (int kk = 0; kk < 4; ++kk) { u32x4 w; w.x = pk2(s[2 * kk][0], s[2 * kk][1]); w.y = pk2(s[2 * kk][2], s[2 * kk][3]); w.z = pk2(s[2 * kk + 1][0], s[2 * kk + 1][1]); w.w = pk2(s[2 * kk + 1][2], s[2 * kk + 1][3]);
;         pf[kk] = __builtin_bit_cast(bf16x8, w); }
;     f32x4 o[8];
; #pragma unroll
;     for (int n = 0; n < 8; ++n) o[n] = (f32x4){0.f, 0.f, 0.f, 0.f};
; #pragma unroll
;     for (int kk = 0; kk < 4; ++kk)
; #pragma unroll
;         for (int n = 0; n < 8; ++n) { const int sw = (2 * n + (fr >> 3)) & 7, jc = kk * 4 + (fq >> 1); const LAS bf16* vr = VT + (n * 16 + fr) * LDT + 4 * (fq & 1);
;             const u32x2 lo = *(const LAS u32x2*)(vr + ((jc ^ sw) << 3)), hi = *(const LAS u32x2*)(vr + (((jc + 2) ^ sw) << 3)); u32x4 w; w.x = lo.x; w.y = lo.y; w.z = hi.x; w.w = hi.y;
;             o[n] = MFMA16(__builtin_bit_cast(bf16x8, w), pf[kk], o[n]); }
	v_mfma_f32_16x16x32_bf16 v[78:81], v[82:85], v[0:3], v[78:81]
	v_cndmask_b32_e64 v49, v105, v230, s[44:45]
	v_cndmask_b32_e64 v82, v105, v230, s[46:47]
	v_cndmask_b32_e64 v83, v105, v230, s[48:49]
	v_mul_f32_e32 v49, v49, v129
	v_mul_f32_e32 v82, v82, v231
	v_mul_f32_e32 v83, v83, v252
	v_exp_f32_e32 v49, v49
	v_exp_f32_e32 v82, v82
	v_exp_f32_e32 v83, v83
	v_pk_mul_f32 v[66:67], v[130:131], v[66:67]
	v_pk_mul_f32 v[48:49], v[48:49], v[50:51]
	v_cndmask_b32_e64 v84, v105, v230, s[50:51]
	v_pk_mul_f32 v[50:51], v[82:83], v[52:53]
	v_cvt_pk_bf16_f32 v52, v66, v67
	v_add_u32_e32 v66, v160, v162
	ds_read_b64 v[66:67], v66
	v_cndmask_b32_e64 v85, v105, v230, s[52:53]
	v_mul_f32_e32 v84, v84, v253
	v_mul_f32_e32 v85, v85, v254
	v_exp_f32_e32 v84, v84
	v_exp_f32_e32 v85, v85
	v_cvt_pk_bf16_f32 v60, v48, v49
	v_cvt_pk_bf16_f32 v61, v50, v51
	v_pk_mul_f32 v[80:81], v[242:243], v[80:81]
	v_pk_mul_f32 v[54:55], v[84:85], v[54:55]
	v_cvt_pk_bf16_f32 v51, v80, v81
	v_cvt_pk_bf16_f32 v62, v54, v55
	v_cvt_pk_bf16_f32 v57, v88, v89
	v_pk_mul_f32 v[78:79], v[240:241], v[78:79]
	s_waitcnt lgkmcnt(0)
	v_mfma_f32_16x16x32_bf16 v[84:87], v[64:67], v[60:63], 0
	v_add_u32_e32 v64, v163, v164
	v_add_u32_e32 v66, v163, v165
	ds_read_b64 v[64:65], v64
	ds_read_b64 v[66:67], v66
	s_waitcnt lgkmcnt(0)
	v_mfma_f32_16x16x32_bf16 v[80:83], v[64:67], v[60:63], 0
	v_add_u32_e32 v64, v166, v167
	v_add_u32_e32 v66, v166, v168
	ds_read_b64 v[64:65], v64
	ds_read_b64 v[66:67], v66
	s_waitcnt lgkmcnt(0)
	v_mfma_f32_16x16x32_bf16 v[88:91], v[64:67], v[60:63], 0
	v_add_u32_e32 v64, v169, v170
	v_add_u32_e32 v66, v169, v171
	ds_read_b64 v[64:65], v64
	ds_read_b64 v[66:67], v66
	v_pk_mul_f32 v[76:77], v[238:239], v[76:77]
	v_cvt_pk_bf16_f32 v50, v78, v79
	v_cvt_pk_bf16_f32 v49, v76, v77
	s_waitcnt lgkmcnt(0)
	v_mfma_f32_16x16x32_bf16 v[76:79], v[64:67], v[60:63], 0
	v_add_u32_e32 v64, v172, v161
	v_add_u32_e32 v66, v172, v162
	ds_read_b64 v[64:65], v64
	ds_read_b64 v[66:67], v66
	v_pk_mul_f32 v[74:75], v[236:237], v[74:75]
	v_pk_mul_f32 v[72:73], v[234:235], v[72:73]
	v_cvt_pk_bf16_f32 v48, v74, v75
	v_cvt_pk_bf16_f32 v55, v72, v73
	s_waitcnt lgkmcnt(0)
	v_mfma_f32_16x16x32_bf16 v[72:75], v[64:67], v[60:63], 0
	v_add_u32_e32 v64, v173, v164
	v_add_u32_e32 v66, v173, v165
	ds_read_b64 v[64:65], v64
	ds_read_b64 v[66:67], v66
	v_pk_mul_f32 v[70:71], v[232:233], v[70:71]
	v_pk_mul_f32 v[68:69], v[132:133], v[68:69]
	v_cvt_pk_bf16_f32 v54, v70, v71
	v_cvt_pk_bf16_f32 v53, v68, v69
	s_waitcnt lgkmcnt(0)
	v_mfma_f32_16x16x32_bf16 v[68:71], v[64:67], v[60:63], 0
	v_add_u32_e32 v64, v174, v167
	v_add_u32_e32 v66, v174, v168
	ds_read_b64 v[64:65], v64
	ds_read_b64 v[66:67], v66
	s_waitcnt lgkmcnt(0)
	v_mfma_f32_16x16x32_bf16 v[64:67], v[64:67], v[60:63], 0
	v_mfma_f32_16x16x32_bf16 v[60:63], v[92:95], v[60:63], 0
	v_add_u32_e32 v92, v160, v176
	v_add_u32_e32 v94, v160, v177
	ds_read_b64 v[92:93], v92
	ds_read_b64 v[94:95], v94
	s_waitcnt lgkmcnt(0)
	v_mfma_f32_16x16x32_bf16 v[84:87], v[92:95], v[56:59], v[84:87]
	v_add_u32_e32 v92, v163, v178
	v_add_u32_e32 v94, v163, v179
	ds_read_b64 v[92:93], v92
	ds_read_b64 v[94:95], v94
	s_waitcnt lgkmcnt(0)
	v_mfma_f32_16x16x32_bf16 v[80:83], v[92:95], v[56:59], v[80:83]
	v_add_u32_e32 v92, v166, v180
	v_add_u32_e32 v94, v166, v181
	ds_read_b64 v[92:93], v92
	ds_read_b64 v[94:95], v94
	s_waitcnt lgkmcnt(0)
	v_mfma_f32_16x16x32_bf16 v[88:91], v[92:95], v[56:59], v[88:91]
	v_add_u32_e32 v92, v169, v182
	v_add_u32_e32 v94, v169, v183
	ds_read_b64 v[92:93], v92
	ds_read_b64 v[94:95], v94
	s_waitcnt lgkmcnt(0)
	v_mfma_f32_16x16x32_bf16 v[92:95], v[92:95], v[56:59], v[76:79]
	s_nop 2
	v_add_u32_e32 v76, v172, v176
	v_add_u32_e32 v78, v172, v177
	ds_read_b64 v[76:77], v76
	ds_read_b64 v[78:79], v78
	s_waitcnt lgkmcnt(0)
	v_mfma_f32_16x16x32_bf16 v[72:75], v[76:79], v[56:59], v[72:75]
	v_add_u32_e32 v76, v173, v178
	v_add_u32_e32 v78, v173, v179
	ds_read_b64 v[76:77], v76
	ds_read_b64 v[78:79], v78
	s_waitcnt lgkmcnt(0)
	v_mfma_f32_16x16x32_bf16 v[68:71], v[76:79], v[56:59], v[68:71]
	v_add_u32_e32 v76, v174, v180
	v_add_u32_e32 v78, v174, v181
	ds_read_b64 v[76:77], v76
	ds_read_b64 v[78:79], v78
	s_waitcnt lgkmcnt(0)
	v_mfma_f32_16x16x32_bf16 v[64:67], v[76:79], v[56:59], v[64:67]
	v_add_u32_e32 v76, v175, v182
	v_add_u32_e32 v78, v175, v183
	ds_read_b64 v[76:77], v76
	ds_read_b64 v[78:79], v78
	s_waitcnt lgkmcnt(0)
	v_mfma_f32_16x16x32_bf16 v[56:59], v[76:79], v[56:59], v[60:63]
	v_add_u32_e32 v76, v163, v186
	v_add_u32_e32 v78, v163, v187
	ds_read_b64 v[76:77], v76
	ds_read_b64 v[78:79], v78
	s_waitcnt lgkmcnt(0)
	v_mfma_f32_16x16x32_bf16 v[76:79], v[76:79], v[52:55], v[80:83]
	s_nop 2
	v_add_u32_e32 v80, v166, v188
	v_add_u32_e32 v82, v166, v189
	ds_read_b64 v[80:81], v80
	ds_read_b64 v[82:83], v82
	s_waitcnt lgkmcnt(0)
	v_mfma_f32_16x16x32_bf16 v[80:83], v[80:83], v[52:55], v[88:91]
	s_nop 2
	v_add_u32_e32 v88, v172, v184
	v_add_u32_e32 v90, v172, v185
	ds_read_b64 v[88:89], v88
	ds_read_b64 v[90:91], v90
	s_waitcnt lgkmcnt(0)
	v_mfma_f32_16x16x32_bf16 v[72:75], v[88:91], v[52:55], v[72:75]
	v_add_u32_e32 v88, v173, v186
	v_add_u32_e32 v90, v173, v187
	v_add_u32_e32 v60, v160, v184
	v_add_u32_e32 v62, v160, v185
	ds_read_b64 v[88:89], v88
	ds_read_b64 v[90:91], v90
	ds_read_b64 v[60:61], v60
	ds_read_b64 v[62:63], v62
	s_waitcnt lgkmcnt(2)
	v_mfma_f32_16x16x32_bf16 v[88:91], v[88:91], v[52:55], v[68:71]
	s_nop 2
	v_add_u32_e32 v68, v174, v188
	v_add_u32_e32 v70, v174, v189
	ds_read_b64 v[68:69], v68
	ds_read_b64 v[70:71], v70
	s_waitcnt lgkmcnt(2)
; #define LAS __attribute__((address_space(3)))
; #define MFMA16(a, b, c) __builtin_amdgcn_mfma_f32_16x16x32_bf16((a), (b), (c), 0, 0, 0)
; __device__ __forceinline__ void ret_unit(LAS unsigned char* lds, int u, const bf16* PROJ, const int* pos, const float* dec_f, const float* dec_b, const bf16* ST,
;                                          const float* gn_w, const float* gn_b, bf16* MIX, int tid, const WsRef& wsr) {
;     ...
; #pragma unroll
;     for (int kk = 0; kk < 4; ++kk)
; #pragma unroll
;         for (int n = 0; n < 8; ++n) { const int sw = (2 * n + (fr >> 3)) & 7, jc = kk * 4 + (fq >> 1); const LAS bf16* vr = VT + (n * 16 + fr) * LDT + 4 * (fq & 1);
;             const u32x2 lo = *(const LAS u32x2*)(vr + ((jc ^ sw) << 3)), hi = *(const LAS u32x2*)(vr + (((jc + 2) ^ sw) << 3)); u32x4 w; w.x = lo.x; w.y = lo.y; w.z = hi.x; w.w = hi.y;
;             o[n] = MFMA16(__builtin_bit_cast(bf16x8, w), pf[kk], o[n]); }
;     __syncthreads();
; #pragma unroll
;     for (int i = 0; i < 4; ++i) { const int id = tid + 512 * i, e = id >> 4, dch = id & 15;
;         *(LAS u32x4*)(Ks + e * LDT + dch * 8) = sf[i]; *(LAS u32x4*)(VT + e * LDT + dch * 8) = sb[i]; }
;     __syncthreads();
;     {
;         f32x4 tf[8], tb[8];
; #pragma unroll
;         for (int n = 0; n < 8; ++n) { tf[n] = (f32x4){0.f, 0.f, 0.f, 0.f}; tb[n] = (f32x4){0.f, 0.f, 0.f, 0.f}; }
; #pragma unroll
;         for (int kk = 0; kk < 4; ++kk)
; #pragma unroll
;             for (int n = 0; n < 8; ++n) { const bf16x8 yf = *(const LAS bf16x8*)(Ks + (n * 16 + fr) * LDT + kk * 32 + fq * 8); const bf16x8 yb = *(const LAS bf16x8*)(VT + (n * 16 + fr) * LDT + kk * 32 + fq * 8);
;                 tf[n] = MFMA16(yf, qf[kk], tf[n]); tb[n] = MFMA16(yb, qf[kk], tb[n]); }
	v_mfma_f32_16x16x32_bf16 v[60:63], v[60:63], v[52:55], v[84:87]
	s_nop 2
	v_add_u32_e32 v84, v169, v190
	v_add_u32_e32 v86, v169, v191
	ds_read_b64 v[84:85], v84
	ds_read_b64 v[86:87], v86
	s_waitcnt lgkmcnt(0)
	v_mfma_f32_16x16x32_bf16 v[84:87], v[84:87], v[52:55], v[92:95]
	v_mfma_f32_16x16x32_bf16 v[92:95], v[68:71], v[52:55], v[64:67]
	v_add_u32_e32 v68, v172, v192
	v_add_u32_e32 v70, v172, v193
	ds_read_b64 v[68:69], v68
	ds_read_b64 v[70:71], v70
	v_add_u32_e32 v64, v175, v190
	v_add_u32_e32 v66, v175, v191
	ds_read_b64 v[64:65], v64
	ds_read_b64 v[66:67], v66
	s_waitcnt lgkmcnt(0)
	v_mfma_f32_16x16x32_bf16 v[232:235], v[64:67], v[52:55], v[56:59]
	v_add_u32_e32 v52, v160, v192
	v_add_u32_e32 v54, v160, v193
	ds_read_b64 v[52:53], v52
	ds_read_b64 v[54:55], v54
	v_add_u32_e32 v56, v163, v194
	v_add_u32_e32 v58, v163, v195
	ds_read_b64 v[56:57], v56
	ds_read_b64 v[58:59], v58
	s_waitcnt lgkmcnt(2)
	v_mfma_f32_16x16x32_bf16 v[52:55], v[52:55], v[48:51], v[60:63]
	s_nop 2
	v_add_u32_e32 v60, v166, v196
	v_add_u32_e32 v62, v166, v197
	ds_read_b64 v[60:61], v60
	ds_read_b64 v[62:63], v62
	v_add_u32_e32 v64, v169, v198
	v_add_u32_e32 v66, v169, v199
	s_waitcnt lgkmcnt(2)
	v_mfma_f32_16x16x32_bf16 v[56:59], v[56:59], v[48:51], v[76:79]
	ds_read_b64 v[64:65], v64
	ds_read_b64 v[66:67], v66
	s_waitcnt lgkmcnt(2)
	v_mfma_f32_16x16x32_bf16 v[60:63], v[60:63], v[48:51], v[80:83]
	v_add_u32_e32 v76, v174, v196
	v_add_u32_e32 v78, v174, v197
	s_nop 0
	v_add_u32_e32 v80, v175, v198
	v_mfma_f32_16x16x32_bf16 v[68:71], v[68:71], v[48:51], v[72:75]
	v_add_u32_e32 v82, v175, v199
	ds_read_b64 v[76:77], v76
	ds_read_b64 v[78:79], v78
	v_add_u32_e32 v72, v173, v194
	v_add_u32_e32 v74, v173, v195
	ds_read_b64 v[72:73], v72
	ds_read_b64 v[74:75], v74
	ds_read_b64 v[80:81], v80
	ds_read_b64 v[82:83], v82
	s_waitcnt lgkmcnt(0)
	s_barrier
	ds_write_b128 v200, v[4:7] offset:34816
	ds_write_b128 v201, v[12:15]
	ds_write_b128 v202, v[8:11] offset:34816
	ds_write_b128 v203, v[16:19]
	ds_write_b128 v205, v[24:27] offset:34816
	ds_write_b128 v206, v[20:23]
	ds_write_b128 v207, v[32:35] offset:34816
	ds_write_b128 v208, v[36:39]
	s_waitcnt lgkmcnt(0)
	s_barrier
	ds_read_b128 v[4:7], v209 offset:34816
	ds_read_b128 v[8:11], v210
	s_waitcnt lgkmcnt(1)
	v_mfma_f32_16x16x32_bf16 v[12:15], v[4:7], v[44:47], 0
	s_waitcnt lgkmcnt(0)
	v_mfma_f32_16x16x32_bf16 v[16:19], v[8:11], v[44:47], 0
	ds_read_b128 v[4:7], v209 offset:39168
	ds_read_b128 v[8:11], v211
	s_waitcnt lgkmcnt(1)
	v_mfma_f32_16x16x32_bf16 v[32:35], v[4:7], v[44:47], 0
	s_waitcnt lgkmcnt(0)
	v_mfma_f32_16x16x32_bf16 v[36:39], v[8:11], v[44:47], 0
	ds_read_b128 v[4:7], v209 offset:43520
	ds_read_b128 v[8:11], v212
	v_mfma_f32_16x16x32_bf16 v[72:75], v[72:75], v[48:51], v[88:91]
	v_mfma_f32_16x16x32_bf16 v[76:79], v[76:79], v[48:51], v[92:95]
	s_waitcnt lgkmcnt(1)
	v_mfma_f32_16x16x32_bf16 v[88:91], v[4:7], v[44:47], 0
	s_waitcnt lgkmcnt(0)
	v_mfma_f32_16x16x32_bf16 v[92:95], v[8:11], v[44:47], 0
	ds_read_b128 v[4:7], v209 offset:47872
	ds_read_b128 v[8:11], v213
	v_mfma_f32_16x16x32_bf16 v[64:67], v[64:67], v[48:51], v[84:87]
	v_mfma_f32_16x16x32_bf16 v[48:51], v[80:83], v[48:51], v[232:235]
	s_waitcnt lgkmcnt(1)
	v_mfma_f32_16x16x32_bf16 v[232:235], v[4:7], v[44:47], 0
	s_waitcnt lgkmcnt(0)
	v_mfma_f32_16x16x32_bf16 v[236:239], v[8:11], v[44:47], 0
	ds_read_b128 v[4:7], v209 offset:52224
	ds_read_b128 v[8:11], v214
	s_waitcnt lgkmcnt(1)
	v_mfma_f32_16x16x32_bf16 v[240:243], v[4:7], v[44:47], 0
	s_waitcnt lgkmcnt(0)
	v_mfma_f32_16x16x32_bf16 v[244:247], v[8:11], v[44:47], 0
	ds_read_b128 v[4:7], v209 offset:56576
	ds_read_b128 v[8:11], v215
	s_waitcnt lgkmcnt(1)
	v_mfma_f32_16x16x32_bf16 v[80:83], v[4:7], v[44:47], 0
	s_waitcnt lgkmcnt(0)
	v_mfma_f32_16x16x32_bf16 v[84:87], v[8:11], v[44:47], 0
	ds_read_b128 v[4:7], v209 offset:60928
	ds_read_b128 v[8:11], v216
	s_waitcnt lgkmcnt(1)
	v_mfma_f32_16x16x32_bf16 v[20:23], v[4:7], v[44:47], 0
	ds_read_b128 v[4:7], v209 offset:65280
	ds_read_b128 v[248:251], v217
	s_waitcnt lgkmcnt(2)
	v_mfma_f32_16x16x32_bf16 v[24:27], v[8:11], v[44:47], 0
	s_waitcnt lgkmcnt(1)
	v_mfma_f32_16x16x32_bf16 v[8:11], v[4:7], v[44:47], 0
	s_waitcnt lgkmcnt(0)
	v_mfma_f32_16x16x32_bf16 v[4:7], v[248:251], v[44:47], 0
	ds_read_b128 v[44:47], v209 offset:34880
	ds_read_b128 v[248:251], v210 offset:64
	s_waitcnt lgkmcnt(1)
	v_mfma_f32_16x16x32_bf16 v[12:15], v[44:47], v[40:43], v[12:15]
	s_waitcnt lgkmcnt(0)
	v_mfma_f32_16x16x32_bf16 v[16:19], v[248:251], v[40:43], v[16:19]
	ds_read_b128 v[44:47], v209 offset:39232
	ds_read_b128 v[248:251], v211 offset:64
	s_waitcnt lgkmcnt(1)
	v_mfma_f32_16x16x32_bf16 v[32:35], v[44:47], v[40:43], v[32:35]
	s_waitcnt lgkmcnt(0)
	v_mfma_f32_16x16x32_bf16 v[36:39], v[248:251], v[40:43], v[36:39]
	ds_read_b128 v[44:47], v209 offset:43584
	ds_read_b128 v[248:251], v212 offset:64
	s_waitcnt lgkmcnt(1)
	v_mfma_f32_16x16x32_bf16 v[44:47], v[44:47], v[40:43], v[88:91]
	s_waitcnt lgkmcnt(0)
	v_mfma_f32_16x16x32_bf16 v[88:91], v[248:251], v[40:43], v[92:95]
	s_nop 2
	ds_read_b128 v[92:95], v209 offset:47936
	ds_read_b128 v[248:251], v213 offset:64
	s_waitcnt lgkmcnt(1)
	v_mfma_f32_16x16x32_bf16 v[92:95], v[92:95], v[40:43], v[232:235]
	s_waitcnt lgkmcnt(0)
	v_mfma_f32_16x16x32_bf16 v[232:235], v[248:251], v[40:43], v[236:239]
	s_nop 2
	ds_read_b128 v[236:239], v209 offset:52288
	ds_read_b128 v[248:251], v214 offset:64
	s_waitcnt lgkmcnt(1)
	v_mfma_f32_16x16x32_bf16 v[236:239], v[236:239], v[40:43], v[240:243]
	s_waitcnt lgkmcnt(0)
	v_mfma_f32_16x16x32_bf16 v[240:243], v[248:251], v[40:43], v[244:247]
	s_nop 2
	ds_read_b128 v[244:247], v209 offset:56640
	ds_read_b128 v[248:251], v215 offset:64
	s_waitcnt lgkmcnt(1)
; #define LAS __attribute__((address_space(3)))
; #define MFMA16(a, b, c) __builtin_amdgcn_mfma_f32_16x16x32_bf16((a), (b), (c), 0, 0, 0)
; __device__ __forceinline__ void ret_unit(LAS unsigned char* lds, int u, const bf16* PROJ, const int* pos, const float* dec_f, const float* dec_b, const bf16* ST,
;                                          const float* gn_w, const float* gn_b, bf16* MIX, int tid, const WsRef& wsr) {
;     ...
; #pragma unroll
;         for (int kk = 0; kk < 4; ++kk)
; #pragma unroll
;             for (int n = 0; n < 8; ++n) { const bf16x8 yf = *(const LAS bf16x8*)(Ks + (n * 16 + fr) * LDT + kk * 32 + fq * 8); const bf16x8 yb = *(const LAS bf16x8*)(VT + (n * 16 + fr) * LDT + kk * 32 + fq * 8);
;                 tf[n] = MFMA16(yf, qf[kk], tf[n]); tb[n] = MFMA16(yb, qf[kk], tb[n]); }
	v_mfma_f32_16x16x32_bf16 v[80:83], v[244:247], v[40:43], v[80:83]
	s_waitcnt lgkmcnt(0)
	v_mfma_f32_16x16x32_bf16 v[84:87], v[248:251], v[40:43], v[84:87]
	ds_read_b128 v[244:247], v209 offset:60992
	ds_read_b128 v[248:251], v216 offset:64
	s_waitcnt lgkmcnt(1)
	v_mfma_f32_16x16x32_bf16 v[244:247], v[244:247], v[40:43], v[20:23]
	s_waitcnt lgkmcnt(0)
	v_mfma_f32_16x16x32_bf16 v[248:251], v[248:251], v[40:43], v[24:27]
	s_nop 0
	ds_read_b128 v[20:23], v209 offset:65344
	s_nop 0
	ds_read_b128 v[24:27], v217 offset:64
	s_waitcnt lgkmcnt(1)
	v_mfma_f32_16x16x32_bf16 v[8:11], v[20:23], v[40:43], v[8:11]
	s_waitcnt lgkmcnt(0)
	v_mfma_f32_16x16x32_bf16 v[4:7], v[24:27], v[40:43], v[4:7]
	ds_read_b128 v[20:23], v209 offset:34944
	ds_read_b128 v[24:27], v210 offset:128
	s_waitcnt lgkmcnt(1)
	v_mfma_f32_16x16x32_bf16 v[40:43], v[20:23], v[28:31], v[12:15]
	s_waitcnt lgkmcnt(0)
	v_mfma_f32_16x16x32_bf16 v[130:133], v[24:27], v[28:31], v[16:19]
	s_nop 0
	ds_read_b128 v[12:15], v209 offset:39296
	s_nop 0
	ds_read_b128 v[16:19], v211 offset:128
	s_waitcnt lgkmcnt(1)
	v_mfma_f32_16x16x32_bf16 v[32:35], v[12:15], v[28:31], v[32:35]
	s_waitcnt lgkmcnt(0)
	v_mfma_f32_16x16x32_bf16 v[36:39], v[16:19], v[28:31], v[36:39]
	ds_read_b128 v[12:15], v209 offset:43648
	ds_read_b128 v[16:19], v212 offset:128
	s_waitcnt lgkmcnt(1)
	v_mfma_f32_16x16x32_bf16 v[44:47], v[12:15], v[28:31], v[44:47]
	s_waitcnt lgkmcnt(0)
	v_mfma_f32_16x16x32_bf16 v[88:91], v[16:19], v[28:31], v[88:91]
	ds_read_b128 v[12:15], v209 offset:48000
	ds_read_b128 v[16:19], v213 offset:128
	s_waitcnt lgkmcnt(1)
	v_mfma_f32_16x16x32_bf16 v[92:95], v[12:15], v[28:31], v[92:95]
	s_waitcnt lgkmcnt(0)
	v_mfma_f32_16x16x32_bf16 v[232:235], v[16:19], v[28:31], v[232:235]
	ds_read_b128 v[12:15], v209 offset:52352
	ds_read_b128 v[16:19], v214 offset:128
	s_waitcnt lgkmcnt(1)
	v_mfma_f32_16x16x32_bf16 v[236:239], v[12:15], v[28:31], v[236:239]
	s_waitcnt lgkmcnt(0)
	v_mfma_f32_16x16x32_bf16 v[240:243], v[16:19], v[28:31], v[240:243]
	ds_read_b128 v[12:15], v209 offset:56704
	ds_read_b128 v[16:19], v215 offset:128
	s_waitcnt lgkmcnt(1)
	v_mfma_f32_16x16x32_bf16 v[20:23], v[12:15], v[28:31], v[80:83]
	s_waitcnt lgkmcnt(0)
	v_mfma_f32_16x16x32_bf16 v[24:27], v[16:19], v[28:31], v[84:87]
	ds_read_b128 v[12:15], v209 offset:61056
	ds_read_b128 v[16:19], v216 offset:128
	ds_read_b128 v[80:83], v209 offset:65408
	ds_read_b128 v[84:87], v217 offset:128
	s_waitcnt lgkmcnt(3)
	v_mfma_f32_16x16x32_bf16 v[12:15], v[12:15], v[28:31], v[244:247]
	s_waitcnt lgkmcnt(2)
	v_mfma_f32_16x16x32_bf16 v[16:19], v[16:19], v[28:31], v[248:251]
	s_waitcnt lgkmcnt(1)
	v_mfma_f32_16x16x32_bf16 v[8:11], v[80:83], v[28:31], v[8:11]
	s_waitcnt lgkmcnt(0)
	v_mfma_f32_16x16x32_bf16 v[4:7], v[84:87], v[28:31], v[4:7]
	ds_read_b128 v[28:31], v209 offset:35008
	ds_read_b128 v[80:83], v210 offset:192
	s_waitcnt lgkmcnt(1)
	v_mfma_f32_16x16x32_bf16 v[28:31], v[28:31], v[0:3], v[40:43]
	s_waitcnt lgkmcnt(0)
	v_mfma_f32_16x16x32_bf16 v[40:43], v[80:83], v[0:3], v[130:133]
	ds_read_b128 v[80:83], v209 offset:39360
	ds_read_b128 v[84:87], v211 offset:192
	s_waitcnt lgkmcnt(1)
	v_mfma_f32_16x16x32_bf16 v[80:83], v[80:83], v[0:3], v[32:35]
	s_waitcnt lgkmcnt(0)
	v_mfma_f32_16x16x32_bf16 v[34:37], v[84:87], v[0:3], v[36:39]
	ds_read_b128 v[84:87], v209 offset:43712
	ds_read_b128 v[130:133], v212 offset:192
	s_waitcnt lgkmcnt(1)
	v_mfma_f32_16x16x32_bf16 v[44:47], v[84:87], v[0:3], v[44:47]
	s_waitcnt lgkmcnt(0)
	v_mfma_f32_16x16x32_bf16 v[84:87], v[130:133], v[0:3], v[88:91]
	s_nop 2
	ds_read_b128 v[88:91], v209 offset:48064
	ds_read_b128 v[130:133], v213 offset:192
	s_waitcnt lgkmcnt(1)
	v_mfma_f32_16x16x32_bf16 v[88:91], v[88:91], v[0:3], v[92:95]
	s_waitcnt lgkmcnt(0)
	v_mfma_f32_16x16x32_bf16 v[92:95], v[130:133], v[0:3], v[232:235]
	ds_read_b128 v[130:133], v209 offset:52416
	s_nop 1
	ds_read_b128 v[232:235], v214 offset:192
	s_waitcnt lgkmcnt(1)
	v_mfma_f32_16x16x32_bf16 v[130:133], v[130:133], v[0:3], v[236:239]
	s_waitcnt lgkmcnt(0)
	v_mfma_f32_16x16x32_bf16 v[232:235], v[232:235], v[0:3], v[240:243]
	s_nop 0
	ds_read_b128 v[236:239], v209 offset:56768
	s_nop 0
	ds_read_b128 v[240:243], v215 offset:192
	s_waitcnt lgkmcnt(1)
	v_mfma_f32_16x16x32_bf16 v[236:239], v[236:239], v[0:3], v[20:23]
	s_waitcnt lgkmcnt(0)
	v_mfma_f32_16x16x32_bf16 v[240:243], v[240:243], v[0:3], v[24:27]
	s_nop 0
	ds_read_b128 v[20:23], v209 offset:61120
	s_nop 0
	ds_read_b128 v[24:27], v216 offset:192
	s_waitcnt lgkmcnt(1)
	v_mfma_f32_16x16x32_bf16 v[12:15], v[20:23], v[0:3], v[12:15]
	s_waitcnt lgkmcnt(0)
	v_mfma_f32_16x16x32_bf16 v[244:247], v[24:27], v[0:3], v[16:19]
	s_nop 2
	ds_read_b128 v[16:19], v209 offset:65472
	ds_read_b128 v[20:23], v217 offset:192
	s_waitcnt lgkmcnt(1)
	v_mfma_f32_16x16x32_bf16 v[8:11], v[16:19], v[0:3], v[8:11]
	s_waitcnt lgkmcnt(0)
; __device__ __forceinline__ float fexp2(float x) { return __builtin_amdgcn_exp2f(x); }
; __device__ __forceinline__ void ret_unit(LAS unsigned char* lds, int u, const bf16* PROJ, const int* pos, const float* dec_f, const float* dec_b, const bf16* ST,
;                                          const float* gn_w, const float* gn_b, bf16* MIX, int tid, const WsRef& wsr) {
;     ...
;         const float xif = fexp2(lgf2 * (float)(q + 1)), xib = fexp2(lgb2 * (float)(128 - q));
; #pragma unroll
;         for (int n = 0; n < 8; ++n) o[n] = o[n] + tf[n] * xif + tb[n] * xib;
;     }
;     float sm = 0.f;
; #pragma unroll
;     for (int n = 0; n < 8; ++n) sm += (o[n][0] + o[n][1]) + (o[n][2] + o[n][3]);
;     sm += __shfl_xor(sm, 16); sm += __shfl_xor(sm, 32);
;     const float mu = sm * (1.f / 128.f);
;     float vq = 0.f;
; #pragma unroll
;     for (int n = 0; n < 8; ++n) { const f32x4 d = o[n] - mu; vq += (d[0] * d[0] + d[1] * d[1]) + (d[2] * d[2] + d[3] * d[3]); }
;     vq += __shfl_xor(vq, 16); vq += __shfl_xor(vq, 32);
	v_mfma_f32_16x16x32_bf16 v[248:251], v[20:23], v[0:3], v[4:7]
	v_mul_f32_e32 v0, v105, v218
	v_exp_f32_e32 v38, v0
	v_mul_f32_e32 v0, v230, v219
	v_exp_f32_e32 v230, v0
	v_pk_fma_f32 v[2:3], v[38:39], v[28:29], v[52:53] op_sel_hi:[0,1,1]
	v_pk_fma_f32 v[16:17], v[38:39], v[132:133], v[70:71] op_sel_hi:[0,1,1]
	v_pk_fma_f32 v[0:1], v[38:39], v[30:31], v[54:55] op_sel_hi:[0,1,1]
	v_pk_fma_f32 v[32:33], v[230:231], v[40:41], v[2:3] op_sel_hi:[0,1,1]
	v_pk_fma_f32 v[2:3], v[38:39], v[80:81], v[56:57] op_sel_hi:[0,1,1]
	v_pk_fma_f32 v[18:19], v[38:39], v[130:131], v[68:69] op_sel_hi:[0,1,1]
	v_pk_fma_f32 v[22:23], v[230:231], v[234:235], v[16:17] op_sel_hi:[0,1,1]
	v_pk_fma_f32 v[16:17], v[38:39], v[238:239], v[74:75] op_sel_hi:[0,1,1]
	v_pk_fma_f32 v[12:13], v[38:39], v[12:13], v[76:77] op_sel_hi:[0,1,1]
	v_pk_fma_f32 v[30:31], v[230:231], v[42:43], v[0:1] op_sel_hi:[0,1,1]
	v_pk_fma_f32 v[0:1], v[38:39], v[82:83], v[58:59] op_sel_hi:[0,1,1]
	v_pk_fma_f32 v[28:29], v[230:231], v[34:35], v[2:3] op_sel_hi:[0,1,1]
	v_pk_fma_f32 v[24:25], v[230:231], v[232:233], v[18:19] op_sel_hi:[0,1,1]
	v_pk_fma_f32 v[18:19], v[230:231], v[242:243], v[16:17] op_sel_hi:[0,1,1]
	v_pk_fma_f32 v[16:17], v[230:231], v[244:245], v[12:13] op_sel_hi:[0,1,1]
	v_pk_fma_f32 v[10:11], v[38:39], v[10:11], v[50:51] op_sel_hi:[0,1,1]
	v_pk_fma_f32 v[12:13], v[38:39], v[8:9], v[48:49] op_sel_hi:[0,1,1]
	v_pk_fma_f32 v[26:27], v[230:231], v[36:37], v[0:1] op_sel_hi:[0,1,1]
	v_pk_fma_f32 v[8:9], v[230:231], v[250:251], v[10:11] op_sel_hi:[0,1,1]
	v_pk_fma_f32 v[10:11], v[230:231], v[248:249], v[12:13] op_sel_hi:[0,1,1]
	v_mov_b32_e32 v12, v32
	v_mov_b32_e32 v13, v28
	v_mov_b32_e32 v34, v33
	v_mov_b32_e32 v35, v29
	v_pk_fma_f32 v[0:1], v[38:39], v[46:47], v[62:63] op_sel_hi:[0,1,1]
	v_pk_fma_f32 v[2:3], v[38:39], v[44:45], v[60:61] op_sel_hi:[0,1,1]
	v_pk_add_f32 v[12:13], v[12:13], v[34:35]
	v_mov_b32_e32 v34, v30
	v_mov_b32_e32 v35, v26
	v_mov_b32_e32 v36, v31
	v_mov_b32_e32 v37, v27
	v_pk_fma_f32 v[4:5], v[230:231], v[86:87], v[0:1] op_sel_hi:[0,1,1]
	v_pk_fma_f32 v[6:7], v[230:231], v[84:85], v[2:3] op_sel_hi:[0,1,1]
	v_pk_add_f32 v[34:35], v[34:35], v[36:37]
	v_mov_b32_e32 v36, v6
	v_pk_add_f32 v[12:13], v[12:13], v[34:35]
	v_pk_mov_b32 v[34:35], v[6:7], v[4:5] op_sel:[1,0]
	v_mov_b32_e32 v37, v5
	v_pk_fma_f32 v[0:1], v[38:39], v[90:91], v[66:67] op_sel_hi:[0,1,1]
	v_pk_fma_f32 v[2:3], v[38:39], v[88:89], v[64:65] op_sel_hi:[0,1,1]
	v_pk_add_f32 v[34:35], v[34:35], v[36:37]
	v_pk_fma_f32 v[0:1], v[230:231], v[94:95], v[0:1] op_sel_hi:[0,1,1]
	v_pk_fma_f32 v[2:3], v[230:231], v[92:93], v[2:3] op_sel_hi:[0,1,1]
	v_add_f32_e32 v12, 0, v12
	v_pk_add_f32 v[34:35], v[34:35], v[34:35] op_sel:[0,1] op_sel_hi:[1,0]
	v_pk_fma_f32 v[20:21], v[38:39], v[236:237], v[72:73] op_sel_hi:[0,1,1]
	v_pk_fma_f32 v[14:15], v[38:39], v[14:15], v[78:79] op_sel_hi:[0,1,1]
	v_add_f32_e32 v12, v12, v13
	v_add_f32_e32 v36, v2, v3
	v_add_f32_e32 v38, v0, v1
	v_mov_b32_e32 v13, v24
	v_mov_b32_e32 v35, v25
	v_mov_b32_e32 v37, v22
	v_mov_b32_e32 v39, v23
	v_pk_fma_f32 v[20:21], v[230:231], v[240:241], v[20:21] op_sel_hi:[0,1,1]
	v_pk_add_f32 v[12:13], v[12:13], v[34:35]
	v_pk_add_f32 v[34:35], v[36:37], v[38:39]
	v_mov_b32_e32 v36, v20
	v_pk_add_f32 v[12:13], v[12:13], v[34:35]
	v_pk_mov_b32 v[34:35], v[20:21], v[18:19] op_sel:[1,0]
	v_mov_b32_e32 v37, v19
	v_pk_add_f32 v[34:35], v[34:35], v[36:37]
	v_pk_fma_f32 v[14:15], v[230:231], v[246:247], v[14:15] op_sel_hi:[0,1,1]
	v_pk_add_f32 v[12:13], v[12:13], v[12:13] op_sel:[0,1] op_sel_hi:[1,0]
	v_pk_add_f32 v[34:35], v[34:35], v[34:35] op_sel:[0,1] op_sel_hi:[1,0]
	v_add_f32_e32 v36, v16, v17
	v_add_f32_e32 v38, v14, v15
	v_mov_b32_e32 v13, v10
	v_mov_b32_e32 v35, v11
	v_mov_b32_e32 v37, v8
	v_mov_b32_e32 v39, v9
	v_pk_add_f32 v[12:13], v[12:13], v[34:35]
	v_pk_add_f32 v[34:35], v[36:37], v[38:39]
	v_or_b32_e32 v48, s0, v126
	v_pk_add_f32 v[12:13], v[12:13], v[34:35]
	v_mov_b32_e32 v49, v97
	v_add_f32_e32 v12, v12, v13
	ds_bpermute_b32 v13, v220, v12
	s_waitcnt lgkmcnt(0)
	v_add_f32_e32 v12, v12, v13
	ds_bpermute_b32 v13, v221, v12
	s_waitcnt lgkmcnt(0)
	v_add_f32_e32 v40, v12, v13
	v_fmamk_f32 v33, v40, 0xbc000000, v33
	v_fmamk_f32 v29, v40, 0xbc000000, v29
	v_fmamk_f32 v31, v40, 0xbc000000, v31
	v_fmac_f32_e32 v32, 0xbc000000, v40
	v_fmamk_f32 v27, v40, 0xbc000000, v27
	v_fmac_f32_e32 v28, 0xbc000000, v40
	v_mov_b32_e32 v34, v33
	v_mov_b32_e32 v35, v29
	v_fmac_f32_e32 v30, 0xbc000000, v40
	v_fmac_f32_e32 v26, 0xbc000000, v40
	v_mov_b32_e32 v12, v32
	v_mov_b32_e32 v13, v28
	v_pk_mul_f32 v[34:35], v[34:35], v[34:35]
	v_mov_b32_e32 v36, v31
	v_mov_b32_e32 v37, v27
	v_pk_fma_f32 v[12:13], v[12:13], v[12:13], v[34:35]
	v_mov_b32_e32 v34, v30
	v_mov_b32_e32 v35, v26
	v_pk_mul_f32 v[36:37], v[36:37], v[36:37]
	v_fmamk_f32 v7, v40, 0xbc000000, v7
	v_pk_fma_f32 v[34:35], v[34:35], v[34:35], v[36:37]
	v_fmac_f32_e32 v6, 0xbc000000, v40
	v_pk_add_f32 v[12:13], v[12:13], v[34:35]
	v_fmamk_f32 v5, v40, 0xbc000000, v5
	v_fmac_f32_e32 v4, 0xbc000000, v40
	v_pk_add_f32 v[12:13], v[12:13], v[12:13] op_sel_hi:[0,1]
	v_pk_mul_f32 v[34:35], v[4:5], v[4:5]
	v_pk_mul_f32 v[36:37], v[6:7], v[6:7]
	v_fmac_f32_e32 v2, 0xbc000000, v40
	v_pk_mov_b32 v[38:39], v[36:37], v[34:35] op_sel:[1,0]
	v_mov_b32_e32 v37, v35
	v_fmamk_f32 v3, v40, 0xbc000000, v3
	v_fmac_f32_e32 v0, 0xbc000000, v40
	v_mul_f32_e32 v12, v2, v2
	v_pk_add_f32 v[34:35], v[38:39], v[36:37]
	v_fmamk_f32 v1, v40, 0xbc000000, v1
	v_pk_fma_f32 v[36:37], v[2:3], v[2:3], v[12:13] op_sel_hi:[1,1,0]
	v_mul_f32_e32 v12, v0, v0
	v_pk_add_f32 v[34:35], v[34:35], v[34:35] op_sel_hi:[0,1]
	v_pk_fma_f32 v[38:39], v[0:1], v[0:1], v[12:13] op_sel_hi:[1,1,0]
; __device__ __forceinline__ unsigned pk2(float lo, float hi) { return pg8::cvt_pk_bf16(lo, hi); }
; __device__ __forceinline__ float bflo(unsigned w) { return __uint_as_float(w << 16); }
; __device__ __forceinline__ float bfhi(unsigned w) { return __uint_as_float(w & 0xffff0000u); }
; __device__ __forceinline__ void ret_unit(LAS unsigned char* lds, int u, const bf16* PROJ, const int* pos, const float* dec_f, const float* dec_b, const bf16* ST,
;                                          const float* gn_w, const float* gn_b, bf16* MIX, int tid, const WsRef& wsr) {
;     ...
;     vq += __shfl_xor(vq, 16); vq += __shfl_xor(vq, 32);
;     const float rstd = rsqrtf(vq * (1.f / 128.f) + EPS);
;     const size_t row = row0 + q;
; #pragma unroll
;     for (int n = 0; n < 8; ++n) { const int col = h * 128 + n * 16 + 4 * fq;
;         const f32x4 gw = *(const f32x4*)(gn_w + col), gb = *(const f32x4*)(gn_b + col);
;         const u32x2 gg = *(const u32x2*)(PROJ + row * INC + 1536 + col);
;         const f32x4 g = (f32x4){bflo(gg.x), bfhi(gg.x), bflo(gg.y), bfhi(gg.y)};
;         f32x4 y = (o[n] - mu) * rstd * gw + gb;
; #pragma unroll
;         for (int r = 0; r < 4; ++r) y[r] = y[r] * g[r] * __builtin_amdgcn_rcpf(1.f + __expf(-g[r]));
;         u32x2 w; w.x = pk2(y[0], y[1]); w.y = pk2(y[2], y[3]); *(u32x2*)(MIX + row * D + col) = w; }
	v_fmamk_f32 v23, v40, 0xbc000000, v23
	v_fmac_f32_e32 v22, 0xbc000000, v40
	v_fmamk_f32 v25, v40, 0xbc000000, v25
	v_fmac_f32_e32 v24, 0xbc000000, v40
	v_mul_f32_e32 v36, v24, v24
	v_mul_f32_e32 v38, v25, v25
	v_mul_f32_e32 v34, v22, v22
	v_mul_f32_e32 v12, v23, v23
	v_pk_add_f32 v[36:37], v[36:37], v[38:39]
	v_pk_add_f32 v[12:13], v[34:35], v[12:13]
	v_fmamk_f32 v21, v40, 0xbc000000, v21
	v_pk_add_f32 v[12:13], v[36:37], v[12:13]
	v_fmac_f32_e32 v20, 0xbc000000, v40
	v_fmamk_f32 v19, v40, 0xbc000000, v19
	v_fmac_f32_e32 v18, 0xbc000000, v40
	v_pk_add_f32 v[12:13], v[12:13], v[12:13] op_sel_hi:[0,1]
	v_pk_mul_f32 v[34:35], v[18:19], v[18:19]
	v_pk_mul_f32 v[36:37], v[20:21], v[20:21]
	v_fmac_f32_e32 v16, 0xbc000000, v40
	v_pk_mov_b32 v[38:39], v[36:37], v[34:35] op_sel:[1,0]
	v_mov_b32_e32 v37, v35
	v_fmamk_f32 v17, v40, 0xbc000000, v17
	v_fmac_f32_e32 v14, 0xbc000000, v40
	v_mul_f32_e32 v12, v16, v16
	v_pk_add_f32 v[34:35], v[38:39], v[36:37]
	v_fmamk_f32 v15, v40, 0xbc000000, v15
	v_pk_fma_f32 v[36:37], v[16:17], v[16:17], v[12:13] op_sel_hi:[1,1,0]
	v_mul_f32_e32 v12, v14, v14
	v_pk_add_f32 v[34:35], v[34:35], v[34:35] op_sel_hi:[0,1]
	v_pk_fma_f32 v[38:39], v[14:15], v[14:15], v[12:13] op_sel_hi:[1,1,0]
	v_fmamk_f32 v9, v40, 0xbc000000, v9
	v_fmac_f32_e32 v8, 0xbc000000, v40
	v_fmamk_f32 v11, v40, 0xbc000000, v11
	v_fmac_f32_e32 v10, 0xbc000000, v40
	v_mul_f32_e32 v36, v10, v10
	v_mul_f32_e32 v38, v11, v11
	v_mul_f32_e32 v34, v8, v8
	v_mul_f32_e32 v12, v9, v9
	v_pk_add_f32 v[36:37], v[36:37], v[38:39]
	v_pk_add_f32 v[12:13], v[34:35], v[12:13]
	v_lshl_add_u64 v[34:35], s[4:5], 0, v[102:103]
	v_pk_add_f32 v[12:13], v[36:37], v[12:13]
	v_mov_b64_e32 v[36:37], s[6:7]
	v_add_f32_e32 v12, v12, v13
	ds_bpermute_b32 v13, v220, v12
	s_waitcnt lgkmcnt(0)
	v_add_f32_e32 v12, v12, v13
	ds_bpermute_b32 v13, v221, v12
	s_waitcnt lgkmcnt(0)
	v_add_f32_e32 v12, v12, v13
	v_fmamk_f32 v12, v12, 0x3c000000, v227
	v_cmp_gt_f32_e64 s[68:69], s1, v12
	v_mul_f32_e32 v13, 0x4b800000, v12
	v_mad_u64_u32 v[44:45], s[0:1], v34, s72, v[36:37]
	v_cndmask_b32_e64 v12, v12, v13, s[68:69]
	v_rsq_f32_e32 v12, v12
	v_mad_i32_i24 v45, v35, s72, v45
	v_lshlrev_b64 v[34:35], 11, v[34:35]
	v_lshl_add_u64 v[46:47], s[70:71], 0, v[34:35]
	v_mul_f32_e32 v13, 0x45800000, v12
	v_cndmask_b32_e64 v12, v12, v13, s[68:69]
	v_lshlrev_b32_e32 v13, 2, v48
	v_lshlrev_b32_e32 v48, 1, v48
	v_lshl_add_u64 v[34:35], v[44:45], 0, v[48:49]
	v_lshl_add_u64 v[46:47], v[46:47], 0, v[48:49]
	global_load_dwordx2 v[56:57], v[34:35], off offset:3072 nt
	global_load_dwordx2 v[58:59], v[34:35], off offset:3104 nt
	global_load_dwordx2 v[60:61], v[34:35], off offset:3136 nt
	global_load_dwordx2 v[62:63], v[34:35], off offset:3168 nt
	global_load_dwordx2 v[64:65], v[34:35], off offset:3200 nt
	global_load_dwordx2 v[66:67], v[34:35], off offset:3232 nt
	global_load_dwordx2 v[68:69], v[34:35], off offset:3264 nt
	global_load_dwordx2 v[70:71], v[34:35], off offset:3296 nt
	global_load_dwordx4 v[72:75], v13, s[22:23]
	global_load_dwordx4 v[76:79], v13, s[36:37]
	global_load_dwordx4 v[80:83], v13, s[22:23] offset:64
	global_load_dwordx4 v[84:87], v13, s[36:37] offset:64
	global_load_dwordx4 v[88:91], v13, s[22:23] offset:128
	global_load_dwordx4 v[92:95], v13, s[36:37] offset:128
	global_load_dwordx4 v[36:39], v13, s[22:23] offset:192
	global_load_dwordx4 v[40:43], v13, s[36:37] offset:192
	global_load_dwordx4 v[232:235], v13, s[22:23] offset:256
	global_load_dwordx4 v[236:239], v13, s[36:37] offset:256
	global_load_dwordx4 v[240:243], v13, s[22:23] offset:320
	global_load_dwordx4 v[248:251], v13, s[36:37] offset:320
	v_pk_mul_f32 v[32:33], v[32:33], v[12:13] op_sel_hi:[1,0]
	v_pk_mul_f32 v[30:31], v[30:31], v[12:13] op_sel_hi:[1,0]
	v_pk_mul_f32 v[28:29], v[28:29], v[12:13] op_sel_hi:[1,0]
	v_pk_mul_f32 v[26:27], v[26:27], v[12:13] op_sel_hi:[1,0]
	v_pk_mul_f32 v[6:7], v[6:7], v[12:13] op_sel_hi:[1,0]
	v_pk_mul_f32 v[4:5], v[4:5], v[12:13] op_sel_hi:[1,0]
	v_pk_mul_f32 v[2:3], v[2:3], v[12:13] op_sel_hi:[1,0]
	v_pk_mul_f32 v[0:1], v[0:1], v[12:13] op_sel_hi:[1,0]
	v_pk_mul_f32 v[24:25], v[24:25], v[12:13] op_sel_hi:[1,0]
	v_pk_mul_f32 v[22:23], v[22:23], v[12:13] op_sel_hi:[1,0]
	v_pk_mul_f32 v[20:21], v[20:21], v[12:13] op_sel_hi:[1,0]
	v_pk_mul_f32 v[18:19], v[18:19], v[12:13] op_sel_hi:[1,0]
	v_pk_mul_f32 v[16:17], v[16:17], v[12:13] op_sel_hi:[1,0]
	v_pk_mul_f32 v[14:15], v[14:15], v[12:13] op_sel_hi:[1,0]
	v_pk_mul_f32 v[10:11], v[10:11], v[12:13] op_sel_hi:[1,0]
	v_pk_mul_f32 v[8:9], v[8:9], v[12:13] op_sel_hi:[1,0]
	s_waitcnt vmcnt(10)
	v_lshlrev_b32_e32 v130, 16, v56
	v_and_b32_e32 v131, 0xffff0000, v56
	v_lshlrev_b32_e32 v132, 16, v57
	v_and_b32_e32 v133, 0xffff0000, v57
	v_pk_fma_f32 v[32:33], v[72:73], v[32:33], v[76:77]
	v_pk_fma_f32 v[30:31], v[74:75], v[30:31], v[78:79]
	global_load_dwordx4 v[72:75], v13, s[22:23] offset:384
	global_load_dwordx4 v[76:79], v13, s[36:37] offset:384
	v_mul_f32_e32 v56, 0xbfb8aa3b, v130
	v_mul_f32_e32 v57, 0xbfb8aa3b, v131
	v_exp_f32_e32 v56, v56
	v_exp_f32_e32 v57, v57
	v_pk_mul_f32 v[32:33], v[32:33], v[130:131]
	v_mul_f32_e32 v130, 0xbfb8aa3b, v132
	v_mul_f32_e32 v131, 0xbfb8aa3b, v133
	v_add_f32_e32 v56, 1.0, v56
	v_add_f32_e32 v57, 1.0, v57
	v_rcp_f32_e32 v56, v56
	v_rcp_f32_e32 v57, v57
	v_exp_f32_e32 v130, v130
	v_exp_f32_e32 v131, v131
	v_pk_mul_f32 v[30:31], v[30:31], v[132:133]
	v_pk_mul_f32 v[32:33], v[56:57], v[32:33]
	v_add_f32_e32 v130, 1.0, v130
	v_add_f32_e32 v131, 1.0, v131
	v_rcp_f32_e32 v130, v130
	v_rcp_f32_e32 v131, v131
	v_cvt_pk_bf16_f32 v56, v32, v33
	s_nop 0
	v_pk_mul_f32 v[30:31], v[130:131], v[30:31]
	s_nop 0
	v_cvt_pk_bf16_f32 v57, v30, v31
	global_store_dwordx2 v[46:47], v[56:57], off
	s_waitcnt vmcnt(11)
; __device__ __forceinline__ unsigned pk2(float lo, float hi) { return pg8::cvt_pk_bf16(lo, hi); }
; __device__ __forceinline__ float bflo(unsigned w) { return __uint_as_float(w << 16); }
; __device__ __forceinline__ float bfhi(unsigned w) { return __uint_as_float(w & 0xffff0000u); }
; __device__ __forceinline__ void ret_unit(LAS unsigned char* lds, int u, const bf16* PROJ, const int* pos, const float* dec_f, const float* dec_b, const bf16* ST,
;                                          const float* gn_w, const float* gn_b, bf16* MIX, int tid, const WsRef& wsr) {
;     ...
;     for (int n = 0; n < 8; ++n) { const int col = h * 128 + n * 16 + 4 * fq;
;         const f32x4 gw = *(const f32x4*)(gn_w + col), gb = *(const f32x4*)(gn_b + col);
;         const u32x2 gg = *(const u32x2*)(PROJ + row * INC + 1536 + col);
;         const f32x4 g = (f32x4){bflo(gg.x), bfhi(gg.x), bflo(gg.y), bfhi(gg.y)};
;         f32x4 y = (o[n] - mu) * rstd * gw + gb;
; #pragma unroll
;         for (int r = 0; r < 4; ++r) y[r] = y[r] * g[r] * __builtin_amdgcn_rcpf(1.f + __expf(-g[r]));
;         u32x2 w; w.x = pk2(y[0], y[1]); w.y = pk2(y[2], y[3]); *(u32x2*)(MIX + row * D + col) = w; }
	v_lshlrev_b32_e32 v130, 16, v58
	v_and_b32_e32 v131, 0xffff0000, v58
	v_lshlrev_b32_e32 v132, 16, v59
	v_and_b32_e32 v133, 0xffff0000, v59
	v_pk_fma_f32 v[28:29], v[80:81], v[28:29], v[84:85]
	v_pk_fma_f32 v[26:27], v[82:83], v[26:27], v[86:87]
	global_load_dwordx4 v[80:83], v13, s[22:23] offset:448
	global_load_dwordx4 v[84:87], v13, s[36:37] offset:448
	v_mul_f32_e32 v58, 0xbfb8aa3b, v130
	v_mul_f32_e32 v59, 0xbfb8aa3b, v131
	v_exp_f32_e32 v58, v58
	v_exp_f32_e32 v59, v59
	v_pk_mul_f32 v[28:29], v[28:29], v[130:131]
	v_mul_f32_e32 v130, 0xbfb8aa3b, v132
	v_mul_f32_e32 v131, 0xbfb8aa3b, v133
	v_add_f32_e32 v58, 1.0, v58
	v_add_f32_e32 v59, 1.0, v59
	v_rcp_f32_e32 v58, v58
	v_rcp_f32_e32 v59, v59
	v_exp_f32_e32 v130, v130
	v_exp_f32_e32 v131, v131
	v_pk_mul_f32 v[26:27], v[26:27], v[132:133]
	v_pk_mul_f32 v[28:29], v[58:59], v[28:29]
	v_add_f32_e32 v130, 1.0, v130
	v_add_f32_e32 v131, 1.0, v131
	v_rcp_f32_e32 v130, v130
	v_rcp_f32_e32 v131, v131
	v_cvt_pk_bf16_f32 v58, v28, v29
	s_nop 0
	v_pk_mul_f32 v[26:27], v[130:131], v[26:27]
	s_nop 0
	v_cvt_pk_bf16_f32 v59, v26, v27
	global_store_dwordx2 v[46:47], v[58:59], off offset:32
	s_waitcnt vmcnt(12)
	v_lshlrev_b32_e32 v130, 16, v60
	v_and_b32_e32 v131, 0xffff0000, v60
	v_lshlrev_b32_e32 v132, 16, v61
	v_and_b32_e32 v133, 0xffff0000, v61
	v_pk_fma_f32 v[6:7], v[88:89], v[6:7], v[92:93]
	v_pk_fma_f32 v[4:5], v[90:91], v[4:5], v[94:95]
	v_mul_f32_e32 v60, 0xbfb8aa3b, v130
	v_mul_f32_e32 v61, 0xbfb8aa3b, v131
	v_exp_f32_e32 v60, v60
	v_exp_f32_e32 v61, v61
	v_pk_mul_f32 v[6:7], v[6:7], v[130:131]
	v_mul_f32_e32 v130, 0xbfb8aa3b, v132
	v_mul_f32_e32 v131, 0xbfb8aa3b, v133
	v_add_f32_e32 v60, 1.0, v60
	v_add_f32_e32 v61, 1.0, v61
	v_rcp_f32_e32 v60, v60
	v_rcp_f32_e32 v61, v61
	v_exp_f32_e32 v130, v130
	v_exp_f32_e32 v131, v131
	v_pk_mul_f32 v[4:5], v[4:5], v[132:133]
	v_pk_mul_f32 v[6:7], v[60:61], v[6:7]
	v_add_f32_e32 v130, 1.0, v130
	v_add_f32_e32 v131, 1.0, v131
	v_rcp_f32_e32 v130, v130
	v_rcp_f32_e32 v131, v131
	v_cvt_pk_bf16_f32 v60, v6, v7
	s_nop 0
	v_pk_mul_f32 v[4:5], v[130:131], v[4:5]
	s_nop 0
	v_cvt_pk_bf16_f32 v61, v4, v5
	global_store_dwordx2 v[46:47], v[60:61], off offset:64
	s_waitcnt vmcnt(11)
	v_lshlrev_b32_e32 v130, 16, v62
	v_and_b32_e32 v131, 0xffff0000, v62
	v_lshlrev_b32_e32 v132, 16, v63
	v_and_b32_e32 v133, 0xffff0000, v63
	v_pk_fma_f32 v[2:3], v[36:37], v[2:3], v[40:41]
	v_pk_fma_f32 v[0:1], v[38:39], v[0:1], v[42:43]
	v_mul_f32_e32 v62, 0xbfb8aa3b, v130
	v_mul_f32_e32 v63, 0xbfb8aa3b, v131
	v_exp_f32_e32 v62, v62
	v_exp_f32_e32 v63, v63
	v_pk_mul_f32 v[2:3], v[2:3], v[130:131]
	v_mul_f32_e32 v130, 0xbfb8aa3b, v132
	v_mul_f32_e32 v131, 0xbfb8aa3b, v133
	v_add_f32_e32 v62, 1.0, v62
	v_add_f32_e32 v63, 1.0, v63
	v_rcp_f32_e32 v62, v62
	v_rcp_f32_e32 v63, v63
	v_exp_f32_e32 v130, v130
	v_exp_f32_e32 v131, v131
	v_pk_mul_f32 v[0:1], v[0:1], v[132:133]
	v_pk_mul_f32 v[2:3], v[62:63], v[2:3]
	v_add_f32_e32 v130, 1.0, v130
	v_add_f32_e32 v131, 1.0, v131
	v_rcp_f32_e32 v130, v130
	v_rcp_f32_e32 v131, v131
	v_cvt_pk_bf16_f32 v62, v2, v3
	s_nop 0
	v_pk_mul_f32 v[0:1], v[130:131], v[0:1]
	s_nop 0
	v_cvt_pk_bf16_f32 v63, v0, v1
	global_store_dwordx2 v[46:47], v[62:63], off offset:96
	s_waitcnt vmcnt(10)
	v_lshlrev_b32_e32 v130, 16, v64
	v_and_b32_e32 v131, 0xffff0000, v64
	v_lshlrev_b32_e32 v132, 16, v65
	v_and_b32_e32 v133, 0xffff0000, v65
	v_pk_fma_f32 v[24:25], v[232:233], v[24:25], v[236:237]
	v_pk_fma_f32 v[22:23], v[234:235], v[22:23], v[238:239]
	v_mul_f32_e32 v64, 0xbfb8aa3b, v130
	v_mul_f32_e32 v65, 0xbfb8aa3b, v131
	v_exp_f32_e32 v64, v64
	v_exp_f32_e32 v65, v65
	v_pk_mul_f32 v[24:25], v[24:25], v[130:131]
	v_mul_f32_e32 v130, 0xbfb8aa3b, v132
	v_mul_f32_e32 v131, 0xbfb8aa3b, v133
	v_add_f32_e32 v64, 1.0, v64
	v_add_f32_e32 v65, 1.0, v65
	v_rcp_f32_e32 v64, v64
	v_rcp_f32_e32 v65, v65
	v_exp_f32_e32 v130, v130
	v_exp_f32_e32 v131, v131
	v_pk_mul_f32 v[22:23], v[22:23], v[132:133]
	v_pk_mul_f32 v[24:25], v[64:65], v[24:25]
	v_add_f32_e32 v130, 1.0, v130
	v_add_f32_e32 v131, 1.0, v131
	v_rcp_f32_e32 v130, v130
	v_rcp_f32_e32 v131, v131
	v_cvt_pk_bf16_f32 v64, v24, v25
	s_nop 0
	v_pk_mul_f32 v[22:23], v[130:131], v[22:23]
	s_nop 0
	v_cvt_pk_bf16_f32 v65, v22, v23
	global_store_dwordx2 v[46:47], v[64:65], off offset:128
	s_waitcnt vmcnt(9)
; __device__ __forceinline__ unsigned pk2(float lo, float hi) { return pg8::cvt_pk_bf16(lo, hi); }
; __device__ __forceinline__ float bflo(unsigned w) { return __uint_as_float(w << 16); }
; __device__ __forceinline__ float bfhi(unsigned w) { return __uint_as_float(w & 0xffff0000u); }
; __device__ __forceinline__ void ret_unit(LAS unsigned char* lds, int u, const bf16* PROJ, const int* pos, const float* dec_f, const float* dec_b, const bf16* ST,
;                                          const float* gn_w, const float* gn_b, bf16* MIX, int tid, const WsRef& wsr) {
;     ...
;     for (int n = 0; n < 8; ++n) { const int col = h * 128 + n * 16 + 4 * fq;
;         const f32x4 gw = *(const f32x4*)(gn_w + col), gb = *(const f32x4*)(gn_b + col);
;         const u32x2 gg = *(const u32x2*)(PROJ + row * INC + 1536 + col);
;         const f32x4 g = (f32x4){bflo(gg.x), bfhi(gg.x), bflo(gg.y), bfhi(gg.y)};
;         f32x4 y = (o[n] - mu) * rstd * gw + gb;
; #pragma unroll
;         for (int r = 0; r < 4; ++r) y[r] = y[r] * g[r] * __builtin_amdgcn_rcpf(1.f + __expf(-g[r]));
;         u32x2 w; w.x = pk2(y[0], y[1]); w.y = pk2(y[2], y[3]); *(u32x2*)(MIX + row * D + col) = w; }
;     __syncthreads();
; __global__ void __launch_bounds__(512, 2) fwd_mega(Args a) {
;     ...
;         for (int u = bid; u < 512; u += G) ret_unit(lds, u, PROJ, pos, a.in[5], a.in[6], ST, a.in[7], a.in[8], MIX, tid, wsr);
	v_lshlrev_b32_e32 v130, 16, v66
	v_and_b32_e32 v131, 0xffff0000, v66
	v_lshlrev_b32_e32 v132, 16, v67
	v_and_b32_e32 v133, 0xffff0000, v67
	v_pk_fma_f32 v[20:21], v[240:241], v[20:21], v[248:249]
	v_pk_fma_f32 v[18:19], v[242:243], v[18:19], v[250:251]
	v_mul_f32_e32 v66, 0xbfb8aa3b, v130
	v_mul_f32_e32 v67, 0xbfb8aa3b, v131
	v_exp_f32_e32 v66, v66
	v_exp_f32_e32 v67, v67
	v_pk_mul_f32 v[20:21], v[20:21], v[130:131]
	v_mul_f32_e32 v130, 0xbfb8aa3b, v132
	v_mul_f32_e32 v131, 0xbfb8aa3b, v133
	v_add_f32_e32 v66, 1.0, v66
	v_add_f32_e32 v67, 1.0, v67
	v_rcp_f32_e32 v66, v66
	v_rcp_f32_e32 v67, v67
	v_exp_f32_e32 v130, v130
	v_exp_f32_e32 v131, v131
	v_pk_mul_f32 v[18:19], v[18:19], v[132:133]
	v_pk_mul_f32 v[20:21], v[66:67], v[20:21]
	v_add_f32_e32 v130, 1.0, v130
	v_add_f32_e32 v131, 1.0, v131
	v_rcp_f32_e32 v130, v130
	v_rcp_f32_e32 v131, v131
	v_cvt_pk_bf16_f32 v66, v20, v21
	s_nop 0
	v_pk_mul_f32 v[18:19], v[130:131], v[18:19]
	s_nop 0
	v_cvt_pk_bf16_f32 v67, v18, v19
	global_store_dwordx2 v[46:47], v[66:67], off offset:160
	s_waitcnt vmcnt(8)
	v_lshlrev_b32_e32 v130, 16, v68
	v_and_b32_e32 v131, 0xffff0000, v68
	v_lshlrev_b32_e32 v132, 16, v69
	v_and_b32_e32 v133, 0xffff0000, v69
	v_pk_fma_f32 v[16:17], v[72:73], v[16:17], v[76:77]
	v_pk_fma_f32 v[14:15], v[74:75], v[14:15], v[78:79]
	v_mul_f32_e32 v68, 0xbfb8aa3b, v130
	v_mul_f32_e32 v69, 0xbfb8aa3b, v131
	v_exp_f32_e32 v68, v68
	v_exp_f32_e32 v69, v69
	v_pk_mul_f32 v[16:17], v[16:17], v[130:131]
	v_mul_f32_e32 v130, 0xbfb8aa3b, v132
	v_mul_f32_e32 v131, 0xbfb8aa3b, v133
	v_add_f32_e32 v68, 1.0, v68
	v_add_f32_e32 v69, 1.0, v69
	v_rcp_f32_e32 v68, v68
	v_rcp_f32_e32 v69, v69
	v_exp_f32_e32 v130, v130
	v_exp_f32_e32 v131, v131
	v_pk_mul_f32 v[14:15], v[14:15], v[132:133]
	v_pk_mul_f32 v[16:17], v[68:69], v[16:17]
	v_add_f32_e32 v130, 1.0, v130
	v_add_f32_e32 v131, 1.0, v131
	v_rcp_f32_e32 v130, v130
	v_rcp_f32_e32 v131, v131
	v_cvt_pk_bf16_f32 v68, v16, v17
	s_nop 0
	v_pk_mul_f32 v[14:15], v[130:131], v[14:15]
	s_nop 0
	v_cvt_pk_bf16_f32 v69, v14, v15
	global_store_dwordx2 v[46:47], v[68:69], off offset:192
	s_waitcnt vmcnt(6)
	v_lshlrev_b32_e32 v130, 16, v70
	v_and_b32_e32 v131, 0xffff0000, v70
	v_lshlrev_b32_e32 v132, 16, v71
	v_and_b32_e32 v133, 0xffff0000, v71
	v_pk_fma_f32 v[10:11], v[80:81], v[10:11], v[84:85]
	v_pk_fma_f32 v[8:9], v[82:83], v[8:9], v[86:87]
	v_mul_f32_e32 v70, 0xbfb8aa3b, v130
	v_mul_f32_e32 v71, 0xbfb8aa3b, v131
	v_exp_f32_e32 v70, v70
	v_exp_f32_e32 v71, v71
	v_pk_mul_f32 v[10:11], v[10:11], v[130:131]
	v_mul_f32_e32 v130, 0xbfb8aa3b, v132
	v_mul_f32_e32 v131, 0xbfb8aa3b, v133
	v_add_f32_e32 v70, 1.0, v70
	v_add_f32_e32 v71, 1.0, v71
	v_rcp_f32_e32 v70, v70
	v_rcp_f32_e32 v71, v71
	v_exp_f32_e32 v130, v130
	v_exp_f32_e32 v131, v131
	v_pk_mul_f32 v[8:9], v[8:9], v[132:133]
	v_pk_mul_f32 v[10:11], v[70:71], v[10:11]
	v_add_f32_e32 v130, 1.0, v130
	v_add_f32_e32 v131, 1.0, v131
	v_rcp_f32_e32 v130, v130
	v_rcp_f32_e32 v131, v131
	v_cvt_pk_bf16_f32 v70, v10, v11
	s_nop 0
	v_pk_mul_f32 v[8:9], v[130:131], v[8:9]
	s_nop 0
	v_cvt_pk_bf16_f32 v71, v8, v9
	global_store_dwordx2 v[46:47], v[70:71], off offset:224
	s_barrier
	s_cbranch_scc1 .LBB0_438
	v_readlane_b32 s82, v255, 40
	v_readlane_b32 s4, v255, 38
	v_readlane_b32 s80, v255, 42
	v_readlane_b32 s83, v255, 41
	v_readlane_b32 s5, v255, 39
	v_readlane_b32 s2, v255, 58
	v_readlane_b32 s81, v255, 43
